# drop conservative vmcnt(0) before attention loops (C, far incl. peeled iteration, B): q loads are already covered by the prologue vmcnt(6)
# baseline (speedup 1.0000x reference)
; template <int MODE, int NQ, int TS, bool FAST = false> ...
;     ...
;   for (int nq = 0; nq < NQ; ++nq) { const bf16_t* qp = proj + (size_t)(seq_base + TS * (q0w + 32 * nq + r32)) * ld + qoff + hh * 8;
; #pragma unroll
;     for (int ks = 0; ks < 4; ++ks) qf[nq][ks] = *(const bf16x8*)(qp + ks * 16); }
;   f32x16 o[NQ][2];
;   float m2[NQ], l[NQ];
; #pragma unroll
;   for (int nq = 0; nq < NQ; ++nq) {
;     if (MODE == 0) {
;       const size_t tok = (size_t)(seq_base + q0w + 32 * nq + r32);
;       const bf16_t* po = part_o + tok * 512 + ooff + 4 * hh; const float* pm = part_ml + (tok * 8 + (ooff >> 6)) * 2;
;       m2[nq] = pm[0]; l[nq] = hh ? 0.f : pm[1];
; #pragma unroll
;       for (int g = 0; g < 4; ++g) { const uint2 a = *(const uint2*)(po + 8 * g), b = *(const uint2*)(po + 32 + 8 * g);
;         o[nq][0][4 * g] = bflo(a.x); o[nq][0][4 * g + 1] = bfhi(a.x); o[nq][0][4 * g + 2] = bflo(a.y); o[nq][0][4 * g + 3] = bfhi(a.y);
;         o[nq][1][4 * g] = bflo(b.x); o[nq][1][4 * g + 1] = bfhi(b.x); o[nq][1][4 * g + 2] = bflo(b.y); o[nq][1][4 * g + 3] = bfhi(b.y); }
;     } else {
;       m2[nq] = (MODE == 2) ? sink2 : -1e30f; l[nq] = 0.f;
; #pragma unroll
;       for (int r = 0; r < 16; ++r) { o[nq][0][r] = 0.f; o[nq][1][r] = 0.f; }
;     }
;   }
;   PG8_LAS unsigned char* L = (PG8_LAS unsigned char*)lds;
;   const int kkey_ = wave * 8 + (lane >> 3);
;   const bf16_t* kg = proj + (size_t)(seq_base + TS * kkey_) * ld + koff + (((lane & 7) ^ ((kkey_ >> 1) & 7)) * 8);
;   const bf16_t* vg = proj + (size_t)(seq_base + TS * ((wave & 3) * 16 + (lane >> 2))) * ld + voff + ((wave >> 2) * 4 + (lane & 3)) * 8;
;   const unsigned sdst = (unsigned)__builtin_amdgcn_readfirstlane(wave * 1024);
;     ...
;   const int ktl = kt1 - 1;
;   constexpr int TAB_OFF = 6 * 16384, TAB_N = (MODE == 3) ? 640 : 1024, TAB_ZERO = TAB_N / 2;
;   if (MODE == 0 || MODE == 3) {
;     float* tab = (float*)(lds + TAB_OFF);
;     for (int e = tid; e < TAB_N; e += 512) {
;       const int oo = e - TAB_ZERO, aa = oo < 0 ? -oo : oo;
;       if (MODE == 0) {
;         const int c = (aa <= 64 ? 1 : 0) + (((oo & 3) == 0 && aa <= 256) ? 1 : 0) + (((oo & 15) == 0 && aa <= 256) ? 1 : 0);
;         tab[e] = c ? (-slope2 * (float)aa + (c == 1 ? 0.f : (c == 2 ? 1.f : 1.5849625007f))) : -1e30f;
;       } else {
;         tab[e] = (aa >= 17 && aa <= 64) ? -slope2 * (float)(16 * aa) : -1e30f;
;       }
;     }
;   }
.LBB0_224:
	s_ashr_i32 s0, s5, 8
	s_lshl_b32 s1, s5, 7
	s_and_b32 s8, s1, 0x7f80
	s_and_b32 s1, s1, 0x7000
	v_lshl_or_b32 v2, s0, 2, v163
	s_cmpk_lt_u32 s8, 0x4000
	v_add_u32_e32 v3, 1, v2
	s_cselect_b32 s7, 0, s1
	v_cvt_f32_i32_e32 v3, v3
	s_cselect_b32 s9, 0x100, 64
	s_sub_i32 s1, s8, s7
	s_add_i32 s8, s1, 0xffffff80
	s_ashr_i32 s8, s8, 6
	s_max_i32 s14, s8, 0
	s_add_i32 s8, s1, 0xff
	v_add_u32_e32 v0, s1, v165
	v_mul_f32_e32 v4, -0.5, v3
	s_mov_b32 s1, 0xc2fc0000
	v_cmp_gt_f32_e32 vcc, s1, v4
	v_readlane_b32 s80, v253, 16
	v_readlane_b32 s88, v253, 24
	v_cndmask_b32_e32 v4, 0, v233, vcc
	v_fmac_f32_e32 v4, -0.5, v3
	v_exp_f32_e32 v3, v4
	v_not_b32_e32 v4, 63
	v_cndmask_b32_e32 v4, 0, v4, vcc
	v_readlane_b32 s89, v253, 25
	v_ldexp_f32 v10, v3, v4
	v_ashrrev_i32_e32 v3, 31, v2
	v_lshlrev_b32_e32 v168, 6, v2
	v_lshl_add_u64 v[2:3], v[2:3], 2, s[88:89]
	global_load_dword v250, v[2:3], off
	v_mov_b32_e32 v3, v222
	s_ashr_i32 s8, s8, 6
	s_add_i32 s12, s8, 1
	v_bfe_u32 v184, v3, 5, 1
	v_ashrrev_i32_e32 v169, 31, v168
	s_cmp_lt_i32 s8, s9
	v_lshl_add_u64 v[6:7], v[168:169], 1, s[66:67]
	s_cselect_b32 s15, s12, s9
	s_movk_i32 s12, 0xc00
	v_and_b32_e32 v13, 3, v3
	s_mov_b32 s1, 0x1ffffffc
	v_mul_f32_e32 v10, 0xbfb8aa3b, v10
	s_lshl_b32 s0, s0, 6
	v_mov_b64_e32 v[4:5], s[66:67]
	s_mov_b64 s[18:19], 0x800
	s_add_i32 s26, s15, -1
	s_mov_b64 s[22:23], 0xa00
	s_mov_b32 s6, 0
	v_readlane_b32 s81, v253, 17
	v_readlane_b32 s82, v253, 18
	v_readlane_b32 s83, v253, 19
	v_readlane_b32 s84, v253, 20
	v_readlane_b32 s85, v253, 21
	v_readlane_b32 s86, v253, 22
	v_readlane_b32 s87, v253, 23
	v_readlane_b32 s90, v253, 26
	v_readlane_b32 s91, v253, 27
	v_readlane_b32 s92, v253, 28
	v_readlane_b32 s93, v253, 29
	v_readlane_b32 s94, v253, 30
	v_readlane_b32 s95, v253, 31
	v_and_b32_e32 v2, 31, v3
	v_or_b32_e32 v0, v0, v2
	v_add_u32_e32 v170, s7, v0
	v_lshlrev_b32_e32 v0, 4, v184
	v_lshl_add_u64 v[6:7], v[6:7], 0, v[0:1]
	v_mad_i64_i32 v[8:9], s[8:9], v170, s12, v[6:7]
	global_load_dwordx4 v[130:133], v[8:9], off
	global_load_dwordx4 v[134:137], v[8:9], off offset:32
	global_load_dwordx4 v[138:141], v[8:9], off offset:64
	global_load_dwordx4 v[142:145], v[8:9], off offset:96
	v_or_b32_e32 v166, 32, v170
	v_ashrrev_i32_e32 v8, 6, v3
	v_mad_i64_i32 v[6:7], s[8:9], v166, s12, v[6:7]
	v_and_b32_e32 v11, 3, v8
	global_load_dwordx4 v[146:149], v[6:7], off
	global_load_dwordx4 v[150:153], v[6:7], off offset:32
	global_load_dwordx4 v[154:157], v[6:7], off offset:64
	global_load_dwordx4 v[158:161], v[6:7], off offset:96
	v_lshlrev_b32_e32 v6, 4, v11
	v_bfe_u32 v7, v3, 2, 4
	v_or3_b32 v6, v6, v7, s7
	v_mul_u32_u24_e32 v12, 0x600, v6
	v_and_or_b32 v6, v8, s1, v13
	v_readfirstlane_b32 s1, v8
	s_lshl_b32 s16, s1, 10
	v_lshlrev_b32_e32 v14, 4, v8
	s_movk_i32 s1, 0xffc0
	v_bfi_b32 v14, s1, v14, v3
	s_movk_i32 s1, 0x100
	v_add_u32_e32 v15, 0xffffff00, v14
	v_cmp_gt_i32_e32 vcc, s1, v14
	v_sub_u32_e32 v16, 0x100, v14
	s_movk_i32 s8, 0x81
	v_cndmask_b32_e32 v15, v15, v16, vcc
	v_cmp_gt_i32_e32 vcc, s8, v15
	v_cvt_f32_i32_e32 v15, v15
	v_lshlrev_b32_e32 v11, 11, v11
	v_lshlrev_b32_e32 v16, 2, v14
	s_mov_b32 s1, 0x18000
	v_mul_f32_e32 v15, v10, v15
	v_add3_u32 v11, v16, v11, s1
	s_movk_i32 s1, 0x80
	v_cndmask_b32_e32 v15, v231, v15, vcc
	v_add_u32_e32 v16, 0xffffff80, v14
	v_cmp_gt_i32_e32 vcc, s1, v14
	v_sub_u32_e32 v17, 0x80, v14
	v_bfe_u32 v0, v3, 3, 3
	v_cndmask_b32_e32 v16, v16, v17, vcc
	v_cmp_gt_i32_e32 vcc, s8, v16
	v_cvt_f32_i32_e32 v16, v16
	v_lshl_or_b32 v0, v8, 3, v0
	s_movk_i32 s1, 0xff80
	v_add_u32_e32 v9, s7, v0
	v_mul_f32_e32 v16, v10, v16
	v_cndmask_b32_e32 v16, v231, v16, vcc
	ds_write2st64_b32 v11, v15, v16 offset1:2
	v_cmp_gt_i32_e32 vcc, 0, v8
	v_sub_u32_e32 v15, 0, v14
	v_lshrrev_b32_e32 v0, 1, v0
	v_cndmask_b32_e32 v15, v14, v15, vcc
	v_cmp_gt_i32_e32 vcc, s8, v15
	v_cvt_f32_i32_e32 v15, v15
	v_add_u32_e32 v16, 0x80, v14
	v_xor_b32_e32 v0, v0, v3
	v_lshlrev_b32_e32 v0, 4, v0
	v_mul_f32_e32 v15, v10, v15
	v_cndmask_b32_e32 v15, v231, v15, vcc
	v_cmp_gt_i32_e32 vcc, s1, v14
	v_sub_u32_e32 v14, 0xffffff80, v14
	s_ashr_i32 s1, s0, 31
	v_cndmask_b32_e32 v14, v16, v14, vcc
	v_cmp_gt_i32_e32 vcc, s8, v14
	v_mad_i64_i32 v[4:5], s[8:9], v9, s12, v[4:5]
	s_lshl_b64 s[0:1], s[0:1], 1
	v_cvt_f32_i32_e32 v14, v14
	v_lshl_add_u64 v[4:5], v[4:5], 0, s[0:1]
	v_and_b32_e32 v0, 0x70, v0
	v_lshl_add_u64 v[172:173], v[4:5], 0, v[0:1]
	v_lshlrev_b32_e32 v0, 1, v12
	v_lshlrev_b32_e32 v6, 3, v6
	v_lshl_add_u64 v[4:5], s[66:67], 0, v[0:1]
	v_ashrrev_i32_e32 v7, 31, v6
	v_lshl_add_u64 v[4:5], v[4:5], 0, s[0:1]
	v_mul_f32_e32 v10, v10, v14
	v_lshl_add_u64 v[174:175], v[6:7], 1, v[4:5]
	v_mad_u64_u32 v[4:5], s[0:1], s14, v232, v[172:173]
	v_cndmask_b32_e32 v10, v231, v10, vcc
	v_lshl_add_u64 v[4:5], v[4:5], 0, s[18:19]
	s_mov_b32 m0, s16
	ds_write2st64_b32 v11, v15, v10 offset0:4 offset1:6
	global_load_lds_dwordx4 v[4:5], off
	v_mad_u64_u32 v[4:5], s[0:1], s14, v232, v[174:175]
	s_or_b32 s0, s14, 1
	v_lshl_add_u64 v[4:5], v[4:5], 0, s[22:23]
	s_add_i32 m0, s16, 0x2000
	s_min_i32 s8, s0, s26
	global_load_lds_dwordx4 v[4:5], off
	v_mad_i64_i32 v[4:5], s[0:1], s8, v232, v[172:173]
	v_lshl_add_u64 v[4:5], v[4:5], 0, s[18:19]
	s_add_i32 m0, s16, 0x4000
	v_lshlrev_b32_e32 v0, 4, v3
	global_load_lds_dwordx4 v[4:5], off
	v_mad_i64_i32 v[4:5], s[0:1], s8, v232, v[174:175]
	s_add_i32 s0, s14, 2
	v_lshl_add_u64 v[4:5], v[4:5], 0, s[22:23]
	s_add_i32 m0, s16, 0x6000
	s_min_i32 s8, s0, s26
	global_load_lds_dwordx4 v[4:5], off
	v_mad_i64_i32 v[4:5], s[0:1], s8, v232, v[172:173]
	v_lshl_add_u64 v[4:5], v[4:5], 0, s[18:19]
	s_add_i32 m0, s16, 0x8000
	v_and_b32_e32 v0, 0xc0, v0
	global_load_lds_dwordx4 v[4:5], off
	v_mad_i64_i32 v[4:5], s[0:1], s8, v232, v[174:175]
	s_add_i32 s0, s14, 3
	v_lshl_add_u64 v[4:5], v[4:5], 0, s[22:23]
	s_add_i32 m0, s16, 0xa000
	s_min_i32 s8, s0, s26
	global_load_lds_dwordx4 v[4:5], off
	v_mad_i64_i32 v[4:5], s[0:1], s8, v232, v[172:173]
	v_lshl_add_u64 v[4:5], v[4:5], 0, s[18:19]
	s_add_i32 m0, s16, 0xc000
	v_lshl_or_b32 v0, v184, 8, v0
	global_load_lds_dwordx4 v[4:5], off
	v_mad_i64_i32 v[4:5], s[0:1], s8, v232, v[174:175]
	v_lshl_add_u64 v[4:5], v[4:5], 0, s[22:23]
	s_add_i32 m0, s16, 0xe000
	v_cmp_lt_i32_e64 s[38:39], 3, v8
	global_load_lds_dwordx4 v[4:5], off
	s_waitcnt vmcnt(6) lgkmcnt(0)
	s_barrier
; template <int MODE, int NQ, int TS, bool FAST = false> ...
;     ...
;       m2[nq] = (MODE == 2) ? sink2 : -1e30f; l[nq] = 0.f;
; #pragma unroll
;       for (int r = 0; r < 16; ++r) { o[nq][0][r] = 0.f; o[nq][1][r] = 0.f; }
;     ...
;   int kfo4[4];
; #pragma unroll
;   for (int ks = 0; ks < 4; ++ks) kfo4[ks] = r32 * 128 + (((2 * ks + hh) ^ ((r32 >> 1) & 7)) << 4);
;   const int vfo = 8192 + (4 * hh + ((lane & 15) >> 2)) * 64 + ((lane >> 4) & 1) * 32 + (lane & 3) * 8;
;   const bool g2 = wave >= 4;
;   f32x16 s[NQ][2];
;   bf16x8 pf[NQ][4];
	v_mul_f32_e32 v183, 0x3fb8aa3b, v250
	v_lshlrev_b32_e32 v4, 1, v3
	v_and_b32_e32 v4, 32, v4
	v_lshlrev_b32_e32 v5, 3, v13
	v_or3_b32 v188, v0, v4, v5
	v_cmp_gt_i32_e64 s[40:41], 4, v8
	s_cmp_ge_i32 s14, s15
	s_cbranch_scc1 .LBB0_242
	v_lshrrev_b32_e32 v0, 1, v3
	v_lshlrev_b32_e32 v6, 7, v2
	v_bitop3_b32 v0, v184, v0, 7 bitop3:0x78
	v_lshl_or_b32 v191, v0, 4, v6
	v_lshlrev_b32_e32 v0, 2, v184
	v_add3_u32 v0, v182, s7, v0
	s_and_b32 s0, s4, 0x7f80
	v_bfe_u32 v4, v3, 1, 3
	v_lshlrev_b32_e32 v3, 5, v3
	v_sub_u32_e32 v0, v0, v2
	v_bitop3_b32 v5, v184, v4, 6 bitop3:0x36
	v_and_b32_e32 v3, 0x1800, v3
	v_subrev_u32_e32 v0, s0, v0
	v_lshl_or_b32 v167, v5, 4, v6
	v_bitop3_b32 v5, v184, v4, 4 bitop3:0x36
	v_bitop3_b32 v4, v184, v4, 2 bitop3:0x36
	v_lshl_add_u32 v3, s14, 8, v3
	v_lshlrev_b32_e32 v0, 2, v0
	s_mov_b32 s0, 0x18380
	v_mov_b32_e32 v14, v1
	v_mov_b32_e32 v15, v1
	v_lshl_or_b32 v171, v5, 4, v6
	v_lshl_or_b32 v190, v4, 4, v6
	v_add3_u32 v192, v3, v0, s0
	v_mov_b32_e32 v0, v1
	v_mov_b32_e32 v2, v1
	v_mov_b32_e32 v3, v1
	v_mov_b32_e32 v4, v1
	v_mov_b32_e32 v5, v1
	v_mov_b32_e32 v6, v1
	v_mov_b32_e32 v7, v1
	v_mov_b32_e32 v8, v1
	v_mov_b32_e32 v9, v1
	v_mov_b32_e32 v10, v1
	v_mov_b32_e32 v11, v1
	v_mov_b32_e32 v12, v1
	v_mov_b32_e32 v13, v1
	v_mov_b64_e32 v[64:65], v[14:15]
	v_mov_b64_e32 v[48:49], v[14:15]
	v_mov_b64_e32 v[32:33], v[14:15]
	v_mov_b64_e32 v[62:63], v[12:13]
	v_mov_b64_e32 v[60:61], v[10:11]
	v_mov_b64_e32 v[58:59], v[8:9]
	v_mov_b64_e32 v[56:57], v[6:7]
	v_mov_b64_e32 v[54:55], v[4:5]
	v_mov_b64_e32 v[52:53], v[2:3]
	v_mov_b64_e32 v[50:51], v[0:1]
	v_mov_b64_e32 v[46:47], v[12:13]
	v_mov_b64_e32 v[44:45], v[10:11]
	v_mov_b64_e32 v[42:43], v[8:9]
	v_mov_b64_e32 v[40:41], v[6:7]
	v_mov_b64_e32 v[38:39], v[4:5]
	v_mov_b64_e32 v[36:37], v[2:3]
	v_mov_b64_e32 v[34:35], v[0:1]
	v_mov_b64_e32 v[30:31], v[12:13]
	v_mov_b64_e32 v[28:29], v[10:11]
	v_mov_b64_e32 v[26:27], v[8:9]
	v_mov_b64_e32 v[24:25], v[6:7]
	v_mov_b64_e32 v[22:23], v[4:5]
	v_mov_b64_e32 v[20:21], v[2:3]
	v_mov_b64_e32 v[18:19], v[0:1]
	v_mov_b64_e32 v[16:17], v[14:15]
	s_mov_b32 s0, 0
	v_mov_b32_e32 v185, 0
	v_mov_b32_e32 v187, v183
	v_mov_b32_e32 v189, v183
	v_mov_b32_e32 v186, 0
	v_mov_b64_e32 v[14:15], v[12:13]
	v_mov_b64_e32 v[12:13], v[10:11]
	v_mov_b64_e32 v[10:11], v[8:9]
	v_mov_b64_e32 v[8:9], v[6:7]
	v_mov_b64_e32 v[6:7], v[4:5]
	v_mov_b64_e32 v[4:5], v[2:3]
	v_mov_b64_e32 v[2:3], v[0:1]
	s_mov_b32 s27, s14
	s_mov_b32 s12, 0xf149f2ca
; template <int MODE, int NQ, int TS, bool FAST = false> ...
;     ...
;   auto QK = [&](int slot) {
;     const char* kb_ = lds + slot * 16384;
; #pragma unroll
;     for (int nq = 0; nq < NQ; ++nq)
; #pragma unroll
;       for (int r = 0; r < 16; ++r) { s[nq][0][r] = 0.f; s[nq][1][r] = 0.f; }
; #pragma unroll
;     for (int ks = 0; ks < 4; ++ks) {
;       const bf16x8 k0 = *(const bf16x8*)(kb_ + kfo4[ks]), k1 = *(const bf16x8*)(kb_ + kfo4[ks] + 4096);
; #pragma unroll
;       for (int nq = 0; nq < NQ; ++nq) { s[nq][0] = MFMA32(k0, qf[nq][ks], s[nq][0]); s[nq][1] = MFMA32(k1, qf[nq][ks], s[nq][1]); }
;     }
;   };
;   auto SM = [&](int kt) {
; #pragma unroll
;     for (int nq = 0; nq < NQ; ++nq) {
;       f32x16& s0 = s[nq][0]; f32x16& s1 = s[nq][1];
;       float mx = -1e30f;
;       if (MODE == 1) {
;       } else if (MODE == 0 || MODE == 3) {
;         const float* tb = (const float*)(lds + TAB_OFF) + (kt * 64 + 4 * hh - (q0w + 32 * nq + r32) + TAB_ZERO);
; #pragma unroll
;         for (int r = 0; r < 16; ++r) {
;           const float va = fmaf(s0[r], C2, tb[(r & 3) + 8 * (r >> 2)]), vb = fmaf(s1[r], C2, tb[(r & 3) + 8 * (r >> 2) + 32]);
;           s0[r] = va; s1[r] = vb; mx = fmaxf(mx, fmaxf(va, vb));
;         }
;       } else {
;         const float* tb = (const float*)(lds + TAB_OFF) + (wave & 3) * 512 + (kt * 64 + 4 * hh - (q0w + 32 * nq + r32) + 256);
; #pragma unroll
;         for (int r = 0; r < 16; ++r) {
;           const float va = fmaf(s0[r], C2, tb[(r & 3) + 8 * (r >> 2)]), vb = fmaf(s1[r], C2, tb[(r & 3) + 8 * (r >> 2) + 32]);
;           s0[r] = va; s1[r] = vb; mx = fmaxf(mx, fmaxf(va, vb));
;         }
;       }
;       float mn;
;       if (MODE == 1) {
;         mn = sink2;
;       } else {
;         if (__any(mx > m2[nq] + 8.f)) {
;           mx = fmaxf(mx, __shfl_xor(mx, 32));
;           mn = fmaxf(m2[nq], mx);
;           const float alpha = __builtin_amdgcn_exp2f(m2[nq] - mn);
;           l[nq] *= alpha;
; #pragma unroll
;           for (int r = 0; r < 16; ++r) { o[nq][0][r] *= alpha; o[nq][1][r] *= alpha; }
;           m2[nq] = mn;
;         }
;     ...
;     { const int tn = (kt + 4 < ktl) ? kt + 4 : ktl; int s4 = slot + 4; if (s4 >= NS) s4 -= NS; ATT_ISSUE(tn, s4); }
;     const bool act = tile_active(kt);
;     if (!g2) {
;       if (act) { QK(slot); SM(kt); PV(slot); }
.LBB0_226:
	s_mov_b32 s28, s0
	s_add_i32 s0, s27, 4
	s_min_i32 s7, s0, s26
	s_cmp_gt_i32 s28, 1
	s_cselect_b32 s0, -2, 4
	s_add_i32 s8, s0, s28
	v_mad_i64_i32 v[98:99], s[0:1], s7, v232, v[172:173]
	s_lshl_b32 s0, s8, 14
	s_add_i32 s8, s16, s0
	v_lshl_add_u64 v[98:99], v[98:99], 0, s[18:19]
	s_mov_b32 m0, s8
	v_add_f32_e32 v0, 0x41000000, v189
	global_load_lds_dwordx4 v[98:99], off
	v_mad_i64_i32 v[98:99], s[0:1], s7, v232, v[174:175]
	v_lshl_add_u64 v[98:99], v[98:99], 0, s[22:23]
	s_add_i32 m0, s8, 0x2000
	s_nop 0
	global_load_lds_dwordx4 v[98:99], off
	s_and_saveexec_b64 s[0:1], s[40:41]
	s_xor_b64 s[0:1], exec, s[0:1]
	s_cbranch_execz .LBB0_232
	s_lshl_b32 s7, s28, 14
	v_or_b32_e32 v70, s7, v191
	ds_read_b128 v[66:69], v70
	ds_read_b128 v[70:73], v70 offset:4096
	v_or_b32_e32 v180, s7, v190
	ds_read_b128 v[176:179], v180
	ds_read_b128 v[194:197], v180 offset:4096
	v_or_b32_e32 v180, s7, v171
	s_waitcnt lgkmcnt(0)
	v_mfma_f32_32x32x16_bf16 v[98:113], v[66:69], v[130:133], 0
	v_mfma_f32_32x32x16_bf16 v[114:129], v[70:73], v[130:133], 0
	v_mfma_f32_32x32x16_bf16 v[82:97], v[66:69], v[146:149], 0
	v_mfma_f32_32x32x16_bf16 v[66:81], v[70:73], v[146:149], 0
	v_mfma_f32_32x32x16_bf16 v[98:113], v[176:179], v[134:137], v[98:113]
	v_mfma_f32_32x32x16_bf16 v[114:129], v[194:197], v[134:137], v[114:129]
	v_mfma_f32_32x32x16_bf16 v[82:97], v[176:179], v[150:153], v[82:97]
	v_mfma_f32_32x32x16_bf16 v[66:81], v[194:197], v[150:153], v[66:81]
	ds_read_b128 v[176:179], v180
	ds_read_b128 v[194:197], v180 offset:4096
	v_or_b32_e32 v180, s7, v167
	s_waitcnt lgkmcnt(0)
	v_mfma_f32_32x32x16_bf16 v[98:113], v[176:179], v[138:141], v[98:113]
	v_mfma_f32_32x32x16_bf16 v[114:129], v[194:197], v[138:141], v[114:129]
	v_mfma_f32_32x32x16_bf16 v[82:97], v[176:179], v[154:157], v[82:97]
	v_mfma_f32_32x32x16_bf16 v[66:81], v[194:197], v[154:157], v[66:81]
	ds_read_b128 v[176:179], v180
	ds_read_b128 v[194:197], v180 offset:4096
	s_waitcnt lgkmcnt(0)
	v_mfma_f32_32x32x16_bf16 v[98:113], v[176:179], v[142:145], v[98:113]
	v_mfma_f32_32x32x16_bf16 v[114:129], v[194:197], v[142:145], v[114:129]
	v_mfma_f32_32x32x16_bf16 v[82:97], v[176:179], v[158:161], v[82:97]
	ds_read2_b32 v[176:177], v192 offset0:32 offset1:33
	ds_read2_b32 v[178:179], v192 offset0:64 offset1:65
	s_waitcnt lgkmcnt(0)
	s_nop 6
	v_fmamk_f32 v193, v98, 0x3e38aa3b, v176
	v_fmac_f32_e32 v179, 0x3e38aa3b, v115
	v_mfma_f32_32x32x16_bf16 v[66:81], v[194:197], v[158:161], v[66:81]
	v_fmamk_f32 v194, v114, 0x3e38aa3b, v178
	v_fmamk_f32 v178, v99, 0x3e38aa3b, v177
	v_max_f32_e32 v98, v193, v194
	v_max_f32_e32 v99, v178, v179
	v_max3_f32 v180, v98, s12, v99
	ds_read2_b32 v[98:99], v192 offset0:34 offset1:35
	ds_read2_b32 v[114:115], v192 offset0:66 offset1:67
	s_waitcnt lgkmcnt(0)
	v_fmamk_f32 v195, v100, 0x3e38aa3b, v98
	v_fmamk_f32 v196, v116, 0x3e38aa3b, v114
	v_fmamk_f32 v114, v101, 0x3e38aa3b, v99
	v_fmac_f32_e32 v115, 0x3e38aa3b, v117
	v_max_f32_e32 v100, v195, v196
	v_max_f32_e32 v101, v114, v115
	v_max3_f32 v180, v180, v100, v101
	ds_read2_b32 v[100:101], v192 offset0:40 offset1:41
	ds_read2_b32 v[116:117], v192 offset0:72 offset1:73
	s_waitcnt lgkmcnt(0)
	v_fmamk_f32 v197, v102, 0x3e38aa3b, v100
	v_fmamk_f32 v198, v118, 0x3e38aa3b, v116
	v_fmamk_f32 v116, v103, 0x3e38aa3b, v101
	v_fmac_f32_e32 v117, 0x3e38aa3b, v119
	v_max_f32_e32 v102, v197, v198
	v_max_f32_e32 v103, v116, v117
	v_max3_f32 v180, v180, v102, v103
	ds_read2_b32 v[102:103], v192 offset0:42 offset1:43
	ds_read2_b32 v[118:119], v192 offset0:74 offset1:75
	s_waitcnt lgkmcnt(0)
	v_fmamk_f32 v199, v104, 0x3e38aa3b, v102
	v_fmamk_f32 v206, v120, 0x3e38aa3b, v118
	v_fmamk_f32 v204, v105, 0x3e38aa3b, v103
	v_fmac_f32_e32 v119, 0x3e38aa3b, v121
	v_max_f32_e32 v104, v199, v206
	v_max_f32_e32 v105, v204, v119
	v_max3_f32 v180, v180, v104, v105
	ds_read2_b32 v[104:105], v192 offset0:48 offset1:49
	ds_read2_b32 v[120:121], v192 offset0:80 offset1:81
	s_waitcnt lgkmcnt(0)
	v_fmamk_f32 v200, v106, 0x3e38aa3b, v104
	v_fmamk_f32 v201, v122, 0x3e38aa3b, v120
	v_fmamk_f32 v118, v107, 0x3e38aa3b, v105
	v_fmac_f32_e32 v121, 0x3e38aa3b, v123
	v_max_f32_e32 v106, v200, v201
	v_max_f32_e32 v107, v118, v121
	v_max3_f32 v180, v180, v106, v107
	ds_read2_b32 v[106:107], v192 offset0:50 offset1:51
	ds_read2_b32 v[122:123], v192 offset0:82 offset1:83
	s_waitcnt lgkmcnt(0)
	v_fmamk_f32 v202, v108, 0x3e38aa3b, v106
	v_fmamk_f32 v203, v124, 0x3e38aa3b, v122
	v_fmamk_f32 v120, v109, 0x3e38aa3b, v107
	v_fmac_f32_e32 v123, 0x3e38aa3b, v125
	v_max_f32_e32 v108, v202, v203
	v_max_f32_e32 v109, v120, v123
	v_max3_f32 v180, v180, v108, v109
	ds_read2_b32 v[108:109], v192 offset0:56 offset1:57
	ds_read2_b32 v[124:125], v192 offset0:88 offset1:89
	s_waitcnt lgkmcnt(0)
	v_fmamk_f32 v205, v110, 0x3e38aa3b, v108
	v_fmamk_f32 v124, v126, 0x3e38aa3b, v124
	v_fmamk_f32 v122, v111, 0x3e38aa3b, v109
	v_fmac_f32_e32 v125, 0x3e38aa3b, v127
	v_max_f32_e32 v110, v205, v124
	v_max_f32_e32 v111, v122, v125
	v_max3_f32 v180, v180, v110, v111
	ds_read2_b32 v[110:111], v192 offset0:58 offset1:59
	ds_read2_b32 v[126:127], v192 offset0:90 offset1:91
	s_waitcnt lgkmcnt(0)
	v_fmamk_f32 v207, v112, 0x3e38aa3b, v110
	v_fmamk_f32 v208, v128, 0x3e38aa3b, v126
	v_fmamk_f32 v126, v113, 0x3e38aa3b, v111
	v_fmac_f32_e32 v127, 0x3e38aa3b, v129
	v_max_f32_e32 v112, v207, v208
	v_max_f32_e32 v113, v126, v127
	v_max3_f32 v112, v180, v112, v113
	v_cmp_gt_f32_e32 vcc, v112, v0
	s_cbranch_vccz .LBB0_229
	v_xor_b32_e32 v0, 32, v223
	v_cmp_lt_i32_e32 vcc, v0, v225
	s_nop 1
	v_cndmask_b32_e32 v0, v223, v0, vcc
	v_lshlrev_b32_e32 v0, 2, v0
	ds_bpermute_b32 v0, v0, v112
	s_waitcnt lgkmcnt(0)
	v_max3_f32 v112, v189, v112, v0
	v_sub_f32_e32 v0, v189, v112
	v_exp_f32_e32 v0, v0
	v_mov_b32_e32 v189, v112
	v_mul_f32_e32 v186, v186, v0
	v_pk_mul_f32 v[64:65], v[64:65], v[0:1] op_sel_hi:[1,0]
	v_pk_mul_f32 v[62:63], v[62:63], v[0:1] op_sel_hi:[1,0]
	v_pk_mul_f32 v[60:61], v[60:61], v[0:1] op_sel_hi:[1,0]
	v_pk_mul_f32 v[58:59], v[58:59], v[0:1] op_sel_hi:[1,0]
	v_pk_mul_f32 v[56:57], v[56:57], v[0:1] op_sel_hi:[1,0]
	v_pk_mul_f32 v[54:55], v[54:55], v[0:1] op_sel_hi:[1,0]
	v_pk_mul_f32 v[52:53], v[52:53], v[0:1] op_sel_hi:[1,0]
	v_pk_mul_f32 v[50:51], v[50:51], v[0:1] op_sel_hi:[1,0]
	v_pk_mul_f32 v[48:49], v[48:49], v[0:1] op_sel_hi:[1,0]
	v_pk_mul_f32 v[46:47], v[46:47], v[0:1] op_sel_hi:[1,0]
	v_pk_mul_f32 v[44:45], v[44:45], v[0:1] op_sel_hi:[1,0]
	v_pk_mul_f32 v[42:43], v[42:43], v[0:1] op_sel_hi:[1,0]
	v_pk_mul_f32 v[40:41], v[40:41], v[0:1] op_sel_hi:[1,0]
	v_pk_mul_f32 v[38:39], v[38:39], v[0:1] op_sel_hi:[1,0]
	v_pk_mul_f32 v[36:37], v[36:37], v[0:1] op_sel_hi:[1,0]
	v_pk_mul_f32 v[34:35], v[34:35], v[0:1] op_sel_hi:[1,0]

; template <int MODE, int NQ, int TS, bool FAST = false> ...
;     ...
;   const int kkey_ = wave * 8 + (lane >> 3);
;   const bf16_t* kg = proj + (size_t)(seq_base + TS * kkey_) * ld + koff + (((lane & 7) ^ ((kkey_ >> 1) & 7)) * 8);
;   const bf16_t* vg = proj + (size_t)(seq_base + TS * ((wave & 3) * 16 + (lane >> 2))) * ld + voff + ((wave >> 2) * 4 + (lane & 3)) * 8;
;   const unsigned sdst = (unsigned)__builtin_amdgcn_readfirstlane(wave * 1024);
;     ...
;   const int ktl = kt1 - 1;
;   constexpr int TAB_OFF = 6 * 16384, TAB_N = (MODE == 3) ? 640 : 1024, TAB_ZERO = TAB_N / 2;
;   if (MODE == 0 || MODE == 3) {
;     float* tab = (float*)(lds + TAB_OFF);
;     for (int e = tid; e < TAB_N; e += 512) {
;       const int oo = e - TAB_ZERO, aa = oo < 0 ? -oo : oo;
;       if (MODE == 0) {
;         const int c = (aa <= 64 ? 1 : 0) + (((oo & 3) == 0 && aa <= 256) ? 1 : 0) + (((oo & 15) == 0 && aa <= 256) ? 1 : 0);
;         tab[e] = c ? (-slope2 * (float)aa + (c == 1 ? 0.f : (c == 2 ? 1.f : 1.5849625007f))) : -1e30f;
;       } else {
;         tab[e] = (aa >= 17 && aa <= 64) ? -slope2 * (float)(16 * aa) : -1e30f;
;       }
;     }
;   }
;   if (MODE == 2) {
;     float* tab = (float*)(lds + TAB_OFF) + (wave & 3) * 512;
; #pragma unroll
;     for (int i = 0; i < 4; ++i) { const int e = (wave >> 2) * 64 + lane + 128 * i; const int oo = e - 256, aa = oo < 0 ? -oo : oo; tab[e] = (aa <= 128) ? -slope2 * (float)aa : -1e30f; }
;   }
;   ATT_ISSUE(kt0, 0); ATT_ISSUE((kt0 + 1 < ktl ? kt0 + 1 : ktl), 1); ATT_ISSUE((kt0 + 2 < ktl ? kt0 + 2 : ktl), 2); ATT_ISSUE((kt0 + 3 < ktl ? kt0 + 3 : ktl), 3);
;   asm volatile("s_waitcnt vmcnt(6) lgkmcnt(0)\n\ts_barrier" ::: "memory");
;   int kfo4[4];
; #pragma unroll
;   for (int ks = 0; ks < 4; ++ks) kfo4[ks] = r32 * 128 + (((2 * ks + hh) ^ ((r32 >> 1) & 7)) << 4);
;   const int vfo = 8192 + (4 * hh + ((lane & 15) >> 2)) * 64 + ((lane >> 4) & 1) * 32 + (lane & 3) * 8;
;   const bool g2 = wave >= 4;
;     ...
;   for (int kt = kt0; kt < kt1; ++kt) {
;     { const int tn = (kt + 4 < ktl) ? kt + 4 : ktl; int s4 = slot + 4; if (s4 >= NS) s4 -= NS; ATT_ISSUE(tn, s4); }
;     const bool act = tile_active(kt);
;     if (!g2) {
;       if (act) { QK(slot); SM(kt); PV(slot); }
;     } else {
;       if (kt > kt0 && tile_active(kt - 1)) PV(sp);
;       if (act) { QK(slot); SM(kt); }
.LBB0_266:
	s_or_b64 exec, exec, s[28:29]
	s_sub_i32 s0, s7, 64
	v_and_b32_e32 v103, 63, v2
	s_ashr_i32 s14, s0, 6
	s_add_i32 s0, s7, 0x13f
	s_lshr_b32 s0, s0, 6
	v_lshrrev_b32_e32 v0, 3, v103
	s_max_i32 s8, s14, 0
	s_or_b32 s1, s0, 1
	v_lshl_or_b32 v0, v10, 3, v0
	s_cmp_lt_u32 s0, s6
	v_lshl_add_u32 v3, v0, 4, s5
	v_mov_b64_e32 v[4:5], s[66:67]
	v_lshrrev_b32_e32 v0, 1, v0
	s_cselect_b32 s15, s1, s6
	v_mad_i64_i32 v[4:5], s[0:1], v3, s24, v[4:5]
	v_xor_b32_e32 v0, v0, v2
	s_lshl_b64 s[0:1], s[40:41], 1
	v_lshlrev_b32_e32 v0, 4, v0
	v_lshl_add_u64 v[4:5], v[4:5], 0, s[0:1]
	v_and_b32_e32 v0, 0x70, v0
	v_lshl_add_u64 v[98:99], v[4:5], 0, v[0:1]
	v_lshlrev_b32_e32 v0, 4, v10
	v_lshrrev_b32_e32 v3, 2, v103
	v_and_or_b32 v0, v0, 48, v3
	v_lshl_add_u32 v0, v0, 4, s5
	s_movk_i32 s5, 0x900
	v_mul_lo_u32 v0, v0, s5
	v_lshl_add_u64 v[4:5], v[0:1], 1, s[66:67]
	v_lshl_add_u64 v[4:5], v[4:5], 0, s[0:1]
	v_and_b32_e32 v0, 3, v2
	s_mov_b32 s0, 0x1ffffffc
	v_and_or_b32 v3, v10, s0, v0
	v_lshlrev_b32_e32 v6, 3, v3
	v_ashrrev_i32_e32 v7, 31, v6
	v_lshl_add_u64 v[100:101], v[6:7], 1, v[4:5]
	s_lshl_b32 s16, s9, 10
	v_mad_u64_u32 v[4:5], s[0:1], s8, v235, v[98:99]
	v_lshl_add_u64 v[4:5], v[4:5], 0, s[60:61]
	s_mov_b32 m0, s16
	s_add_i32 s5, s15, -1
	global_load_lds_dwordx4 v[4:5], off
	v_mad_u64_u32 v[4:5], s[0:1], s8, v235, v[100:101]
	s_add_i32 s6, s8, 1
	v_lshl_add_u64 v[4:5], v[4:5], 0, s[58:59]
	s_add_i32 m0, s16, 0x2000
	s_min_u32 s7, s6, s5
	global_load_lds_dwordx4 v[4:5], off
	v_mad_u64_u32 v[4:5], s[0:1], s7, v235, v[98:99]
	v_lshl_add_u64 v[4:5], v[4:5], 0, s[60:61]
	s_add_i32 m0, s16, 0x4000
	v_lshlrev_b32_e32 v3, 4, v2
	global_load_lds_dwordx4 v[4:5], off
	v_mad_u64_u32 v[4:5], s[0:1], s7, v235, v[100:101]
	s_add_i32 s0, s8, 2
	v_lshl_add_u64 v[4:5], v[4:5], 0, s[58:59]
	s_add_i32 m0, s16, 0x6000
	s_min_u32 s7, s0, s5
	global_load_lds_dwordx4 v[4:5], off
	v_mad_u64_u32 v[4:5], s[0:1], s7, v235, v[98:99]
	v_lshl_add_u64 v[4:5], v[4:5], 0, s[60:61]
	s_add_i32 m0, s16, 0x8000
	v_and_b32_e32 v3, 0xc0, v3
	global_load_lds_dwordx4 v[4:5], off
	v_mad_u64_u32 v[4:5], s[0:1], s7, v235, v[100:101]
	s_add_i32 s0, s8, 3
	v_lshl_add_u64 v[4:5], v[4:5], 0, s[58:59]
	s_add_i32 m0, s16, 0xa000
	s_min_u32 s7, s0, s5
	global_load_lds_dwordx4 v[4:5], off
	v_mad_u64_u32 v[4:5], s[0:1], s7, v235, v[98:99]
	v_lshl_add_u64 v[4:5], v[4:5], 0, s[60:61]
	s_add_i32 m0, s16, 0xc000
	v_lshl_or_b32 v3, v105, 8, v3
	global_load_lds_dwordx4 v[4:5], off
	v_mad_u64_u32 v[4:5], s[0:1], s7, v235, v[100:101]
	v_lshl_add_u64 v[4:5], v[4:5], 0, s[58:59]
	s_add_i32 m0, s16, 0xe000
	v_lshlrev_b32_e32 v0, 3, v0
	global_load_lds_dwordx4 v[4:5], off
	s_waitcnt vmcnt(6) lgkmcnt(0)
	s_barrier
	v_lshlrev_b32_e32 v4, 1, v2
	v_and_b32_e32 v4, 32, v4
	s_mov_b32 s9, 0
	v_or3_b32 v106, v3, v4, v0
	v_cmp_lt_i32_e64 s[36:37], 3, v10
	v_cmp_gt_i32_e64 s[38:39], 4, v10
	s_cmp_lt_i32 s14, s15
	v_subrev_u32_e32 v107, 64, v9
	v_add_u32_e32 v108, 0x5f, v9
	s_cbranch_scc0 .LBB0_271
	s_add_i32 s0, s8, 4
	s_min_u32 s7, s0, s5
	v_mad_u64_u32 v[4:5], s[0:1], s7, v235, v[98:99]
	v_lshl_add_u64 v[4:5], v[4:5], 0, s[60:61]
	s_add_i32 m0, s16, 0x10000
	v_lshrrev_b32_e32 v0, 1, v2
	global_load_lds_dwordx4 v[4:5], off
	v_mad_u64_u32 v[4:5], s[0:1], s7, v235, v[100:101]
	v_lshl_add_u64 v[4:5], v[4:5], 0, s[58:59]
	s_add_i32 m0, s16, 0x12000
	v_bfe_u32 v2, v2, 1, 3
	global_load_lds_dwordx4 v[4:5], off
	s_lshl_b32 s7, s8, 6
	v_bitop3_b32 v3, v105, v2, 6 bitop3:0x36
	v_lshlrev_b32_e32 v4, 7, v8
	v_bitop3_b32 v0, v105, v0, 7 bitop3:0x78
	s_or_b32 s0, s7, 63
	v_lshl_or_b32 v97, v3, 4, v4
	v_bitop3_b32 v3, v105, v2, 4 bitop3:0x36
	v_bitop3_b32 v2, v105, v2, 2 bitop3:0x36
	v_lshl_or_b32 v111, v0, 4, v4
	v_lshlrev_b32_e32 v0, 2, v105
	v_cmp_ge_i32_e32 vcc, s0, v107
	v_cmp_le_i32_e64 s[0:1], s7, v108
	v_lshl_or_b32 v109, v3, 4, v4
	v_lshl_or_b32 v110, v2, 4, v4
	v_sub_u32_e32 v65, v0, v66
	s_and_b64 s[0:1], vcc, s[0:1]
	s_and_saveexec_b64 s[12:13], s[38:39]
	s_xor_b64 s[78:79], exec, s[12:13]
	s_cbranch_execz .LBB0_275
	v_mov_b32_e32 v14, v1
	v_mov_b32_e32 v15, v1
	v_mov_b32_e32 v0, v1
	v_mov_b32_e32 v2, v1
	v_mov_b32_e32 v3, v1
	v_mov_b32_e32 v4, v1
	v_mov_b32_e32 v5, v1
	v_mov_b32_e32 v6, v1
	v_mov_b32_e32 v7, v1
	v_mov_b32_e32 v8, v1
	v_mov_b32_e32 v9, v1
	v_mov_b32_e32 v10, v1
	v_mov_b32_e32 v11, v1
	v_mov_b32_e32 v12, v1
	v_mov_b32_e32 v13, v1
	v_mov_b64_e32 v[30:31], v[14:15]
	v_mov_b64_e32 v[46:47], v[14:15]
	v_mov_b32_e32 v102, 0xf149f2ca
	v_mov_b32_e32 v112, 0
	v_mov_b64_e32 v[28:29], v[12:13]
	v_mov_b64_e32 v[26:27], v[10:11]
	v_mov_b64_e32 v[24:25], v[8:9]
	v_mov_b64_e32 v[22:23], v[6:7]
	v_mov_b64_e32 v[20:21], v[4:5]
	v_mov_b64_e32 v[18:19], v[2:3]
	v_mov_b64_e32 v[16:17], v[0:1]
	v_mov_b64_e32 v[44:45], v[12:13]
	v_mov_b64_e32 v[42:43], v[10:11]
	v_mov_b64_e32 v[40:41], v[8:9]
	v_mov_b64_e32 v[38:39], v[6:7]
	v_mov_b64_e32 v[36:37], v[4:5]
	v_mov_b64_e32 v[34:35], v[2:3]
	v_mov_b64_e32 v[32:33], v[0:1]
	s_and_saveexec_b64 s[80:81], s[0:1]
	s_cbranch_execz .LBB0_274
; #define MFMA32(a, b, c) __builtin_amdgcn_mfma_f32_32x32x16_bf16((a), (b), (c), 0, 0, 0)
; template <int MODE, int NQ, int TS, bool FAST = false> ...
;     ...
;   auto QK = [&](int slot) {
;     const char* kb_ = lds + slot * 16384;
; #pragma unroll
;     for (int nq = 0; nq < NQ; ++nq)
; #pragma unroll
;       for (int r = 0; r < 16; ++r) { s[nq][0][r] = 0.f; s[nq][1][r] = 0.f; }
; #pragma unroll
;     for (int ks = 0; ks < 4; ++ks) {
;       const bf16x8 k0 = *(const bf16x8*)(kb_ + kfo4[ks]), k1 = *(const bf16x8*)(kb_ + kfo4[ks] + 4096);
; #pragma unroll
;       for (int nq = 0; nq < NQ; ++nq) { s[nq][0] = MFMA32(k0, qf[nq][ks], s[nq][0]); s[nq][1] = MFMA32(k1, qf[nq][ks], s[nq][1]); }
;     }
;   };
;   auto SM = [&](int kt) {
; #pragma unroll
;     for (int nq = 0; nq < NQ; ++nq) {
;       f32x16& s0 = s[nq][0]; f32x16& s1 = s[nq][1];
;       float mx = -1e30f;
;       if (MODE == 1) {
;       } else if (MODE == 0 || MODE == 3) {
;         const float* tb = (const float*)(lds + TAB_OFF) + (kt * 64 + 4 * hh - (q0w + 32 * nq + r32) + TAB_ZERO);
; #pragma unroll
;         for (int r = 0; r < 16; ++r) {
;           const float va = fmaf(s0[r], C2, tb[(r & 3) + 8 * (r >> 2)]), vb = fmaf(s1[r], C2, tb[(r & 3) + 8 * (r >> 2) + 32]);
;           s0[r] = va; s1[r] = vb; mx = fmaxf(mx, fmaxf(va, vb));
;         }
;       } else {
;         const float* tb = (const float*)(lds + TAB_OFF) + (wave & 3) * 512 + (kt * 64 + 4 * hh - (q0w + 32 * nq + r32) + 256);
; #pragma unroll
;         for (int r = 0; r < 16; ++r) {
;           const float va = fmaf(s0[r], C2, tb[(r & 3) + 8 * (r >> 2)]), vb = fmaf(s1[r], C2, tb[(r & 3) + 8 * (r >> 2) + 32]);
;           s0[r] = va; s1[r] = vb; mx = fmaxf(mx, fmaxf(va, vb));
;         }
;       }
;       float mn;
;       if (MODE == 1) {
;         mn = sink2;
;       } else {
;         if (__any(mx > m2[nq] + 8.f)) {
;           mx = fmaxf(mx, __shfl_xor(mx, 32));
;           mn = fmaxf(m2[nq], mx);
;           const float alpha = __builtin_amdgcn_exp2f(m2[nq] - mn);
;           l[nq] *= alpha;
; #pragma unroll
;           for (int r = 0; r < 16; ++r) { o[nq][0][r] *= alpha; o[nq][1][r] *= alpha; }
;           m2[nq] = mn;
;         }
;         mn = m2[nq];
	ds_read_b128 v[2:5], v111
	ds_read_b128 v[18:21], v111 offset:4096
	ds_read_b128 v[34:37], v110
	ds_read_b128 v[38:41], v110 offset:4096
	v_lshlrev_b32_e32 v0, 2, v65
	v_lshl_add_u32 v50, s7, 2, v0
	s_waitcnt lgkmcnt(0)
	v_mfma_f32_32x32x16_bf16 v[2:17], v[2:5], v[80:83], 0
	v_add_u32_e32 v0, 0x18500, v50
	v_mov_b32_e32 v102, 0xf149f2ca
	v_mfma_f32_32x32x16_bf16 v[18:33], v[18:21], v[80:83], 0
	v_mfma_f32_32x32x16_bf16 v[2:17], v[34:37], v[84:87], v[2:17]
	v_mfma_f32_32x32x16_bf16 v[18:33], v[38:41], v[84:87], v[18:33]
	ds_read_b128 v[34:37], v109
	ds_read_b128 v[38:41], v109 offset:4096
	s_waitcnt lgkmcnt(1)
	v_mfma_f32_32x32x16_bf16 v[2:17], v[34:37], v[88:91], v[2:17]
	s_waitcnt lgkmcnt(0)
	v_mfma_f32_32x32x16_bf16 v[18:33], v[38:41], v[88:91], v[18:33]
	ds_read_b128 v[34:37], v97
	ds_read_b128 v[38:41], v97 offset:4096
	s_waitcnt lgkmcnt(1)
	v_mfma_f32_32x32x16_bf16 v[2:17], v[34:37], v[92:95], v[2:17]
	ds_read2_b32 v[34:35], v0 offset1:1
	s_waitcnt lgkmcnt(1)
	v_mfma_f32_32x32x16_bf16 v[18:33], v[38:41], v[92:95], v[18:33]
	s_waitcnt lgkmcnt(0)
	s_nop 7
	v_fmamk_f32 v0, v2, 0x3e38aa3b, v34
	v_add_u32_e32 v2, 0x18580, v50
	ds_read2_b32 v[36:37], v2 offset1:1
	v_fmac_f32_e32 v35, 0x3e38aa3b, v3
	s_waitcnt lgkmcnt(0)
	v_fmamk_f32 v34, v18, 0x3e38aa3b, v36
	v_fmac_f32_e32 v37, 0x3e38aa3b, v19
	v_max_f32_e32 v2, v0, v34
	v_max_f32_e32 v3, v35, v37
	v_max3_f32 v18, v2, v102, v3
	v_add_u32_e32 v2, 0x18508, v50
	ds_read2_b32 v[2:3], v2 offset1:1
	s_waitcnt lgkmcnt(0)
	v_fmamk_f32 v2, v4, 0x3e38aa3b, v2
	v_add_u32_e32 v4, 0x18588, v50
	ds_read2_b32 v[38:39], v4 offset1:1
	v_fmac_f32_e32 v3, 0x3e38aa3b, v5
	s_waitcnt lgkmcnt(0)
	v_fmamk_f32 v38, v20, 0x3e38aa3b, v38
	v_fmac_f32_e32 v39, 0x3e38aa3b, v21
	v_max_f32_e32 v4, v2, v38
	v_max_f32_e32 v5, v3, v39
	v_max3_f32 v18, v18, v4, v5
	v_add_u32_e32 v4, 0x18520, v50
	ds_read2_b32 v[4:5], v4 offset1:1
	s_waitcnt lgkmcnt(0)
	v_fmamk_f32 v4, v6, 0x3e38aa3b, v4
	v_add_u32_e32 v6, 0x185a0, v50
	ds_read2_b32 v[40:41], v6 offset1:1
	v_fmac_f32_e32 v5, 0x3e38aa3b, v7
	s_waitcnt lgkmcnt(0)
	v_fmamk_f32 v36, v22, 0x3e38aa3b, v40
	v_fmac_f32_e32 v41, 0x3e38aa3b, v23
	v_max_f32_e32 v6, v4, v36
	v_max_f32_e32 v7, v5, v41
	v_max3_f32 v18, v18, v6, v7
	v_add_u32_e32 v6, 0x18528, v50
	ds_read2_b32 v[6:7], v6 offset1:1
	s_waitcnt lgkmcnt(0)
	v_fmamk_f32 v6, v8, 0x3e38aa3b, v6
	v_add_u32_e32 v8, 0x185a8, v50
	ds_read2_b32 v[42:43], v8 offset1:1
	v_fmac_f32_e32 v7, 0x3e38aa3b, v9
	s_waitcnt lgkmcnt(0)
	v_fmamk_f32 v42, v24, 0x3e38aa3b, v42
	v_fmac_f32_e32 v43, 0x3e38aa3b, v25
	v_max_f32_e32 v8, v6, v42
	v_max_f32_e32 v9, v7, v43
	v_max3_f32 v18, v18, v8, v9
	v_add_u32_e32 v8, 0x18540, v50
	ds_read2_b32 v[8:9], v8 offset1:1
	s_waitcnt lgkmcnt(0)
	v_fmamk_f32 v8, v10, 0x3e38aa3b, v8
	v_add_u32_e32 v10, 0x185c0, v50
	ds_read2_b32 v[44:45], v10 offset1:1
	v_fmac_f32_e32 v9, 0x3e38aa3b, v11
	s_waitcnt lgkmcnt(0)
	v_fmamk_f32 v40, v26, 0x3e38aa3b, v44
	v_fmac_f32_e32 v45, 0x3e38aa3b, v27
	v_max_f32_e32 v10, v8, v40
	v_max_f32_e32 v11, v9, v45
	v_max3_f32 v18, v18, v10, v11
	v_add_u32_e32 v10, 0x18548, v50
	ds_read2_b32 v[10:11], v10 offset1:1
	s_waitcnt lgkmcnt(0)
	v_fmamk_f32 v10, v12, 0x3e38aa3b, v10
	v_add_u32_e32 v12, 0x185c8, v50
	ds_read2_b32 v[46:47], v12 offset1:1
	v_fmac_f32_e32 v11, 0x3e38aa3b, v13
	s_waitcnt lgkmcnt(0)
	v_fmamk_f32 v46, v28, 0x3e38aa3b, v46
	v_fmac_f32_e32 v47, 0x3e38aa3b, v29
	v_max_f32_e32 v12, v10, v46
	v_max_f32_e32 v13, v11, v47
	v_max3_f32 v18, v18, v12, v13
	v_add_u32_e32 v12, 0x18560, v50
	ds_read2_b32 v[12:13], v12 offset1:1
	s_waitcnt lgkmcnt(0)
	v_fmamk_f32 v12, v14, 0x3e38aa3b, v12
	v_add_u32_e32 v14, 0x185e0, v50
	ds_read2_b32 v[48:49], v14 offset1:1
	v_fmac_f32_e32 v13, 0x3e38aa3b, v15
	s_waitcnt lgkmcnt(0)
	v_fmamk_f32 v44, v30, 0x3e38aa3b, v48
	v_fmac_f32_e32 v49, 0x3e38aa3b, v31
	v_max_f32_e32 v14, v12, v44
	v_max_f32_e32 v15, v13, v49
	v_max3_f32 v18, v18, v14, v15
	v_add_u32_e32 v14, 0x18568, v50
	ds_read2_b32 v[14:15], v14 offset1:1
	s_waitcnt lgkmcnt(0)
	v_fmamk_f32 v14, v16, 0x3e38aa3b, v14
	v_add_u32_e32 v16, 0x185e8, v50
	ds_read2_b32 v[50:51], v16 offset1:1
	v_fmac_f32_e32 v15, 0x3e38aa3b, v17
	s_waitcnt lgkmcnt(0)
	v_fmamk_f32 v32, v32, 0x3e38aa3b, v50
	v_fmac_f32_e32 v51, 0x3e38aa3b, v33
	v_max_f32_e32 v16, v14, v32
	v_max_f32_e32 v17, v15, v51
	v_max3_f32 v16, v18, v16, v17
	v_cmp_gt_f32_e32 vcc, v16, v102
	s_cbranch_vccz .LBB0_272
	v_xor_b32_e32 v17, 32, v223
	v_cmp_lt_i32_e32 vcc, v17, v225
	s_nop 1
	v_cndmask_b32_e32 v17, v223, v17, vcc
	v_lshlrev_b32_e32 v17, 2, v17
	ds_bpermute_b32 v17, v17, v16
	s_waitcnt lgkmcnt(0)
	v_max3_f32 v102, v16, v17, s25
	v_sub_f32_e32 v16, 0xf149f2ca, v102
	v_exp_f32_e32 v16, v16
	s_nop 0
	v_mul_f32_e32 v16, 0, v16
	s_branch .LBB0_273

; #define MFMA32(a, b, c) __builtin_amdgcn_mfma_f32_32x32x16_bf16((a), (b), (c), 0, 0, 0)
; template <int MODE, int NQ, int TS, bool FAST = false> ...
;     ...
;   auto QK = [&](int slot) {
;     const char* kb_ = lds + slot * 16384;
; #pragma unroll
;     for (int nq = 0; nq < NQ; ++nq)
; #pragma unroll
;       for (int r = 0; r < 16; ++r) { s[nq][0][r] = 0.f; s[nq][1][r] = 0.f; }
; #pragma unroll
;     for (int ks = 0; ks < 4; ++ks) {
;       const bf16x8 k0 = *(const bf16x8*)(kb_ + kfo4[ks]), k1 = *(const bf16x8*)(kb_ + kfo4[ks] + 4096);
; #pragma unroll
;       for (int nq = 0; nq < NQ; ++nq) { s[nq][0] = MFMA32(k0, qf[nq][ks], s[nq][0]); s[nq][1] = MFMA32(k1, qf[nq][ks], s[nq][1]); }
;     }
;   };
;   auto SM = [&](int kt) {
; #pragma unroll
;     for (int nq = 0; nq < NQ; ++nq) {
;       f32x16& s0 = s[nq][0]; f32x16& s1 = s[nq][1];
;       float mx = -1e30f;
;       if (MODE == 1) {
;       } else if (MODE == 0 || MODE == 3) {
;         const float* tb = (const float*)(lds + TAB_OFF) + (kt * 64 + 4 * hh - (q0w + 32 * nq + r32) + TAB_ZERO);
; #pragma unroll
;         for (int r = 0; r < 16; ++r) {
;           const float va = fmaf(s0[r], C2, tb[(r & 3) + 8 * (r >> 2)]), vb = fmaf(s1[r], C2, tb[(r & 3) + 8 * (r >> 2) + 32]);
;           s0[r] = va; s1[r] = vb; mx = fmaxf(mx, fmaxf(va, vb));
;         }
;       } else {
;         const float* tb = (const float*)(lds + TAB_OFF) + (wave & 3) * 512 + (kt * 64 + 4 * hh - (q0w + 32 * nq + r32) + 256);
; #pragma unroll
;         for (int r = 0; r < 16; ++r) {
;           const float va = fmaf(s0[r], C2, tb[(r & 3) + 8 * (r >> 2)]), vb = fmaf(s1[r], C2, tb[(r & 3) + 8 * (r >> 2) + 32]);
;           s0[r] = va; s1[r] = vb; mx = fmaxf(mx, fmaxf(va, vb));
;         }
;       }
;       float mn;
;       if (MODE == 1) {
;         mn = sink2;
;       } else {
;         if (__any(mx > m2[nq] + 8.f)) {
;           mx = fmaxf(mx, __shfl_xor(mx, 32));
;           mn = fmaxf(m2[nq], mx);
;           const float alpha = __builtin_amdgcn_exp2f(m2[nq] - mn);
;           l[nq] *= alpha;
; #pragma unroll
;           for (int r = 0; r < 16; ++r) { o[nq][0][r] *= alpha; o[nq][1][r] *= alpha; }
;           m2[nq] = mn;
;         }
;         mn = m2[nq];
;     ...
;       if (kt > kt0 && tile_active(kt - 1)) PV(sp);
;       if (act) { QK(slot); SM(kt); }
.LBB0_275:
	s_andn2_saveexec_b64 s[28:29], s[78:79]
	s_cbranch_execz .LBB0_282
	v_mov_b32_e32 v14, v1
	v_mov_b32_e32 v15, v1
	v_mov_b32_e32 v0, v1
	v_mov_b32_e32 v2, v1
	v_mov_b32_e32 v3, v1
	v_mov_b32_e32 v4, v1
	v_mov_b32_e32 v5, v1
	v_mov_b32_e32 v6, v1
	v_mov_b32_e32 v7, v1
	v_mov_b32_e32 v8, v1
	v_mov_b32_e32 v9, v1
	v_mov_b32_e32 v10, v1
	v_mov_b32_e32 v11, v1
	v_mov_b32_e32 v12, v1
	v_mov_b32_e32 v13, v1
	v_mov_b64_e32 v[46:47], v[14:15]
	v_mov_b32_e32 v102, 0xf149f2ca
	v_mov_b32_e32 v112, 0
	v_mov_b64_e32 v[44:45], v[12:13]
	v_mov_b64_e32 v[42:43], v[10:11]
	v_mov_b64_e32 v[40:41], v[8:9]
	v_mov_b64_e32 v[38:39], v[6:7]
	v_mov_b64_e32 v[36:37], v[4:5]
	v_mov_b64_e32 v[34:35], v[2:3]
	v_mov_b64_e32 v[32:33], v[0:1]
	s_and_saveexec_b64 s[30:31], s[0:1]
	s_cbranch_execz .LBB0_281
	ds_read_b128 v[2:5], v111
	ds_read_b128 v[18:21], v111 offset:4096
	ds_read_b128 v[34:37], v110
	ds_read_b128 v[38:41], v110 offset:4096
	v_lshlrev_b32_e32 v0, 2, v65
	v_mov_b32_e32 v102, 0xf149f2ca
	s_waitcnt lgkmcnt(0)
	v_mfma_f32_32x32x16_bf16 v[2:17], v[2:5], v[80:83], 0
	v_mfma_f32_32x32x16_bf16 v[18:33], v[18:21], v[80:83], 0
	v_mfma_f32_32x32x16_bf16 v[2:17], v[34:37], v[84:87], v[2:17]
	v_mfma_f32_32x32x16_bf16 v[18:33], v[38:41], v[84:87], v[18:33]
	ds_read_b128 v[34:37], v109
	ds_read_b128 v[38:41], v109 offset:4096
	s_waitcnt lgkmcnt(1)
	v_mfma_f32_32x32x16_bf16 v[2:17], v[34:37], v[88:91], v[2:17]
	s_waitcnt lgkmcnt(0)
	v_mfma_f32_32x32x16_bf16 v[18:33], v[38:41], v[88:91], v[18:33]
	ds_read_b128 v[34:37], v97
	ds_read_b128 v[38:41], v97 offset:4096
	s_waitcnt lgkmcnt(1)
	v_mfma_f32_32x32x16_bf16 v[2:17], v[34:37], v[92:95], v[2:17]
	v_lshl_add_u32 v34, s7, 2, v0
	v_add_u32_e32 v0, 0x18500, v34
	ds_read2_b32 v[48:49], v0 offset1:1
	s_waitcnt lgkmcnt(1)
	v_mfma_f32_32x32x16_bf16 v[18:33], v[38:41], v[92:95], v[18:33]
	s_waitcnt lgkmcnt(0)
	s_nop 5
	v_fmamk_f32 v0, v2, 0x3e38aa3b, v48
	v_add_u32_e32 v2, 0x18580, v34
	ds_read2_b32 v[50:51], v2 offset1:1
	v_fmac_f32_e32 v49, 0x3e38aa3b, v3
	s_waitcnt lgkmcnt(0)
	v_fmamk_f32 v48, v18, 0x3e38aa3b, v50
	v_fmac_f32_e32 v51, 0x3e38aa3b, v19
	v_max_f32_e32 v2, v0, v48
	v_max_f32_e32 v3, v49, v51
	v_max3_f32 v35, v2, v102, v3
	v_add_u32_e32 v2, 0x18508, v34
	ds_read2_b32 v[2:3], v2 offset1:1
	s_waitcnt lgkmcnt(0)
	v_fmamk_f32 v2, v4, 0x3e38aa3b, v2
	v_add_u32_e32 v4, 0x18588, v34
	ds_read2_b32 v[18:19], v4 offset1:1
	v_fmac_f32_e32 v3, 0x3e38aa3b, v5
	s_waitcnt lgkmcnt(0)
	v_fmamk_f32 v18, v20, 0x3e38aa3b, v18
	v_fmac_f32_e32 v19, 0x3e38aa3b, v21
	v_max_f32_e32 v4, v2, v18
	v_max_f32_e32 v5, v3, v19
	v_max3_f32 v35, v35, v4, v5
	v_add_u32_e32 v4, 0x18520, v34
	ds_read2_b32 v[4:5], v4 offset1:1
	s_waitcnt lgkmcnt(0)
	v_fmamk_f32 v4, v6, 0x3e38aa3b, v4
	v_add_u32_e32 v6, 0x185a0, v34
	ds_read2_b32 v[20:21], v6 offset1:1
	v_fmac_f32_e32 v5, 0x3e38aa3b, v7
	s_waitcnt lgkmcnt(0)
	v_fmamk_f32 v20, v22, 0x3e38aa3b, v20
	v_fmac_f32_e32 v21, 0x3e38aa3b, v23
	v_max_f32_e32 v6, v4, v20
	v_max_f32_e32 v7, v5, v21
	v_max3_f32 v35, v35, v6, v7
	v_add_u32_e32 v6, 0x18528, v34
	ds_read2_b32 v[6:7], v6 offset1:1
	s_waitcnt lgkmcnt(0)
	v_fmamk_f32 v6, v8, 0x3e38aa3b, v6
	v_add_u32_e32 v8, 0x185a8, v34
	ds_read2_b32 v[22:23], v8 offset1:1
	v_fmac_f32_e32 v7, 0x3e38aa3b, v9
	s_waitcnt lgkmcnt(0)
	v_fmamk_f32 v22, v24, 0x3e38aa3b, v22
	v_fmac_f32_e32 v23, 0x3e38aa3b, v25
	v_max_f32_e32 v8, v6, v22
	v_max_f32_e32 v9, v7, v23
	v_max3_f32 v35, v35, v8, v9
	v_add_u32_e32 v8, 0x18540, v34
	ds_read2_b32 v[8:9], v8 offset1:1
	s_waitcnt lgkmcnt(0)
	v_fmamk_f32 v8, v10, 0x3e38aa3b, v8
	v_add_u32_e32 v10, 0x185c0, v34
	ds_read2_b32 v[24:25], v10 offset1:1
	v_fmac_f32_e32 v9, 0x3e38aa3b, v11
	s_waitcnt lgkmcnt(0)
	v_fmamk_f32 v24, v26, 0x3e38aa3b, v24
	v_fmac_f32_e32 v25, 0x3e38aa3b, v27
	v_max_f32_e32 v10, v8, v24
	v_max_f32_e32 v11, v9, v25
	v_max3_f32 v35, v35, v10, v11
	v_add_u32_e32 v10, 0x18548, v34
	ds_read2_b32 v[10:11], v10 offset1:1
	s_waitcnt lgkmcnt(0)
	v_fmamk_f32 v10, v12, 0x3e38aa3b, v10
	v_add_u32_e32 v12, 0x185c8, v34
	ds_read2_b32 v[26:27], v12 offset1:1
	v_fmac_f32_e32 v11, 0x3e38aa3b, v13
	s_waitcnt lgkmcnt(0)
	v_fmamk_f32 v26, v28, 0x3e38aa3b, v26
	v_fmac_f32_e32 v27, 0x3e38aa3b, v29
	v_max_f32_e32 v12, v10, v26
	v_max_f32_e32 v13, v11, v27
	v_max3_f32 v35, v35, v12, v13
	v_add_u32_e32 v12, 0x18560, v34
	ds_read2_b32 v[12:13], v12 offset1:1
	s_waitcnt lgkmcnt(0)
	v_fmamk_f32 v12, v14, 0x3e38aa3b, v12
	v_add_u32_e32 v14, 0x185e0, v34
	ds_read2_b32 v[28:29], v14 offset1:1
	v_fmac_f32_e32 v13, 0x3e38aa3b, v15
	s_waitcnt lgkmcnt(0)
	v_fmamk_f32 v28, v30, 0x3e38aa3b, v28
	v_fmac_f32_e32 v29, 0x3e38aa3b, v31
	v_max_f32_e32 v14, v12, v28
	v_max_f32_e32 v15, v13, v29
	v_max3_f32 v35, v35, v14, v15
	v_add_u32_e32 v14, 0x18568, v34
	ds_read2_b32 v[14:15], v14 offset1:1
	s_waitcnt lgkmcnt(0)
	v_fmamk_f32 v14, v16, 0x3e38aa3b, v14
	v_add_u32_e32 v16, 0x185e8, v34
	ds_read2_b32 v[30:31], v16 offset1:1
	v_fmac_f32_e32 v15, 0x3e38aa3b, v17
	s_waitcnt lgkmcnt(0)
	v_fmamk_f32 v16, v32, 0x3e38aa3b, v30
	v_fmac_f32_e32 v31, 0x3e38aa3b, v33
	v_max_f32_e32 v30, v14, v16
	v_max_f32_e32 v17, v15, v31
	v_max3_f32 v17, v35, v30, v17
	v_cmp_gt_f32_e32 vcc, v17, v102
	s_cbranch_vccz .LBB0_279
	v_xor_b32_e32 v30, 32, v223
	v_cmp_lt_i32_e32 vcc, v30, v225
	s_nop 1
	v_cndmask_b32_e32 v30, v223, v30, vcc
	v_lshlrev_b32_e32 v30, 2, v30
	ds_bpermute_b32 v30, v30, v17
	s_waitcnt lgkmcnt(0)
	v_max3_f32 v102, v17, v30, s25
	v_sub_f32_e32 v17, 0xf149f2ca, v102
	v_exp_f32_e32 v17, v17
	s_nop 0
	v_mul_f32_e32 v32, 0, v17
	v_mov_b32_e32 v33, v32
	v_mov_b32_e32 v34, v32
	v_mov_b32_e32 v35, v32
	v_mov_b32_e32 v36, v32
	v_mov_b32_e32 v37, v32
	v_mov_b32_e32 v38, v32
	v_mov_b32_e32 v39, v32
	v_mov_b32_e32 v40, v32
	v_mov_b32_e32 v41, v32
	v_mov_b32_e32 v42, v32
	v_mov_b32_e32 v43, v32
	v_mov_b32_e32 v44, v32
	v_mov_b32_e32 v45, v32
	v_mov_b32_e32 v46, v32
	v_mov_b32_e32 v47, v32
	v_mov_b32_e32 v17, v32
	s_branch .LBB0_280

; template <int MODE, int NQ, int TS, bool FAST = false> ...
;     ...
;   auto SM = [&](int kt) {
; #pragma unroll
;     for (int nq = 0; nq < NQ; ++nq) {
;       f32x16& s0 = s[nq][0]; f32x16& s1 = s[nq][1];
;       float mx = -1e30f;
;       if (MODE == 1) {
;       } else if (MODE == 0 || MODE == 3) {
;         const float* tb = (const float*)(lds + TAB_OFF) + (kt * 64 + 4 * hh - (q0w + 32 * nq + r32) + TAB_ZERO);
; #pragma unroll
;         for (int r = 0; r < 16; ++r) {
;           const float va = fmaf(s0[r], C2, tb[(r & 3) + 8 * (r >> 2)]), vb = fmaf(s1[r], C2, tb[(r & 3) + 8 * (r >> 2) + 32]);
;           s0[r] = va; s1[r] = vb; mx = fmaxf(mx, fmaxf(va, vb));
;         }
;       } else {
;         const float* tb = (const float*)(lds + TAB_OFF) + (wave & 3) * 512 + (kt * 64 + 4 * hh - (q0w + 32 * nq + r32) + 256);
; #pragma unroll
;         for (int r = 0; r < 16; ++r) {
;           const float va = fmaf(s0[r], C2, tb[(r & 3) + 8 * (r >> 2)]), vb = fmaf(s1[r], C2, tb[(r & 3) + 8 * (r >> 2) + 32]);
;           s0[r] = va; s1[r] = vb; mx = fmaxf(mx, fmaxf(va, vb));
;         }
;       }
;       float mn;
;       if (MODE == 1) {
;         mn = sink2;
;       } else {
;         if (__any(mx > m2[nq] + 8.f)) {
;           mx = fmaxf(mx, __shfl_xor(mx, 32));
;           mn = fmaxf(m2[nq], mx);
;           const float alpha = __builtin_amdgcn_exp2f(m2[nq] - mn);
;           l[nq] *= alpha;
; #pragma unroll
;           for (int r = 0; r < 16; ++r) { o[nq][0][r] *= alpha; o[nq][1][r] *= alpha; }
;           m2[nq] = mn;
;         }
;         mn = m2[nq];
;     ...
;   for (int kt = kt0; kt < kt1; ++kt) {
;     { const int tn = (kt + 4 < ktl) ? kt + 4 : ktl; int s4 = slot + 4; if (s4 >= NS) s4 -= NS; ATT_ISSUE(tn, s4); }
;     const bool act = tile_active(kt);
;     if (!g2) {
;       if (act) { QK(slot); SM(kt); PV(slot); }
;     } else {
;       if (kt > kt0 && tile_active(kt - 1)) PV(sp);
;       if (act) { QK(slot); SM(kt); }
;     }
;     asm volatile("s_waitcnt vmcnt(6) lgkmcnt(0)\n\ts_barrier" ::: "memory");
;     sp = slot; slot = (slot + 1 == NS) ? 0 : slot + 1;
;   }
.LBB0_282:
	s_or_b64 exec, exec, s[28:29]
	s_waitcnt vmcnt(6) lgkmcnt(0)
	s_barrier
	s_cmp_ge_u32 s6, s15
	s_cbranch_scc1 .LBB0_303
	v_lshl_or_b32 v0, s8, 8, v64
	v_lshlrev_b32_e32 v2, 2, v66
	v_sub_u32_e32 v0, v0, v2
	s_add_i32 s6, s8, 5
	v_add_u32_e32 v113, 0x18600, v0
	s_mov_b32 s12, 0
	s_mov_b32 s0, 1
.LBB0_284:
	s_min_i32 s9, s6, s5
	s_cmp_gt_i32 s0, 1
	s_mov_b32 s8, s0
	s_cselect_b32 s0, -2, 4
	s_add_i32 s13, s0, s8
	v_mad_i64_i32 v[2:3], s[0:1], s9, v235, v[98:99]
	s_lshl_b32 s0, s13, 14
	s_add_i32 s13, s16, s0
	v_lshl_add_u64 v[2:3], v[2:3], 0, s[60:61]
	s_mov_b32 m0, s13
	s_nop 0
	global_load_lds_dwordx4 v[2:3], off
	v_mad_i64_i32 v[2:3], s[0:1], s9, v235, v[100:101]
	v_lshl_add_u64 v[2:3], v[2:3], 0, s[58:59]
	s_add_i32 m0, s13, 0x2000
	s_add_i32 s9, s7, 64
	global_load_lds_dwordx4 v[2:3], off
	s_add_i32 s0, s7, 0x7f
	v_cmp_ge_i32_e32 vcc, s0, v107
	v_cmp_le_i32_e64 s[0:1], s9, v108
	s_and_b64 s[78:79], vcc, s[0:1]
	s_and_saveexec_b64 s[0:1], s[38:39]
	s_xor_b64 s[0:1], exec, s[0:1]
	s_cbranch_execz .LBB0_290
	s_and_saveexec_b64 s[80:81], s[78:79]
	s_cbranch_execz .LBB0_289
	ds_read2_b32 v[116:117], v113 offset0:40 offset1:41
	ds_read2_b32 v[118:119], v113 offset1:1
	ds_read2_b32 v[120:121], v113 offset0:32 offset1:33
	ds_read2_b32 v[122:123], v113 offset0:34 offset1:35
	ds_read2_b32 v[124:125], v113 offset0:2 offset1:3
	ds_read2_b32 v[126:127], v113 offset0:42 offset1:43
	ds_read2_b32 v[128:129], v113 offset0:8 offset1:9
	ds_read2_b32 v[130:131], v113 offset0:10 offset1:11
	ds_read2_b32 v[132:133], v113 offset0:48 offset1:49
	ds_read2_b32 v[134:135], v113 offset0:16 offset1:17
	ds_read2_b32 v[136:137], v113 offset0:50 offset1:51
	ds_read2_b32 v[138:139], v113 offset0:18 offset1:19
	ds_read2_b32 v[140:141], v113 offset0:24 offset1:25
	ds_read2_b32 v[142:143], v113 offset0:56 offset1:57
	ds_read2_b32 v[144:145], v113 offset0:26 offset1:27
	ds_read2_b32 v[146:147], v113 offset0:58 offset1:59
	s_lshl_b32 s13, s8, 14
	v_or_b32_e32 v0, s13, v111
	ds_read_b128 v[2:5], v0
	ds_read_b128 v[6:9], v0 offset:4096
	v_or_b32_e32 v0, s13, v110
	s_waitcnt lgkmcnt(0)
	v_mfma_f32_32x32x16_bf16 v[64:79], v[2:5], v[80:83], 0
	v_mfma_f32_32x32x16_bf16 v[48:63], v[6:9], v[80:83], 0
	ds_read_b128 v[2:5], v0
	ds_read_b128 v[6:9], v0 offset:4096
	v_or_b32_e32 v0, s13, v109
	s_waitcnt lgkmcnt(0)
	v_mfma_f32_32x32x16_bf16 v[64:79], v[2:5], v[84:87], v[64:79]
	v_mfma_f32_32x32x16_bf16 v[48:63], v[6:9], v[84:87], v[48:63]
	ds_read_b128 v[2:5], v0
	ds_read_b128 v[6:9], v0 offset:4096
	v_or_b32_e32 v0, s13, v97
	s_waitcnt lgkmcnt(0)
	v_mfma_f32_32x32x16_bf16 v[64:79], v[2:5], v[88:91], v[64:79]
	v_mfma_f32_32x32x16_bf16 v[48:63], v[6:9], v[88:91], v[48:63]
	ds_read_b128 v[2:5], v0
	ds_read_b128 v[6:9], v0 offset:4096
	s_waitcnt lgkmcnt(0)
	v_mfma_f32_32x32x16_bf16 v[64:79], v[2:5], v[92:95], v[64:79]
	v_mfma_f32_32x32x16_bf16 v[48:63], v[6:9], v[92:95], v[48:63]
	s_nop 10
	v_fmamk_f32 v0, v64, 0x3e38aa3b, v118
	v_fmamk_f32 v3, v65, 0x3e38aa3b, v119
	v_fmamk_f32 v2, v48, 0x3e38aa3b, v120
	v_fmamk_f32 v5, v49, 0x3e38aa3b, v121
	v_max_f32_e32 v4, v0, v2
	v_max_f32_e32 v6, v3, v5
	v_max3_f32 v10, v4, s25, v6
	v_fmamk_f32 v9, v51, 0x3e38aa3b, v123
	v_fmamk_f32 v13, v53, 0x3e38aa3b, v117
	v_fmamk_f32 v4, v66, 0x3e38aa3b, v124
	v_fmamk_f32 v6, v50, 0x3e38aa3b, v122
	v_fmamk_f32 v7, v67, 0x3e38aa3b, v125
	v_max_f32_e32 v8, v4, v6
	v_max_f32_e32 v11, v7, v9
	v_max3_f32 v14, v10, v8, v11
	v_fmamk_f32 v49, v55, 0x3e38aa3b, v127
	v_fmamk_f32 v8, v68, 0x3e38aa3b, v128
	v_fmamk_f32 v10, v52, 0x3e38aa3b, v116
	v_fmamk_f32 v11, v69, 0x3e38aa3b, v129
	v_max_f32_e32 v12, v8, v10
	v_max_f32_e32 v15, v11, v13
	v_max3_f32 v50, v14, v12, v15
	v_fmamk_f32 v68, v54, 0x3e38aa3b, v126
	v_fmamk_f32 v12, v70, 0x3e38aa3b, v130
	v_fmamk_f32 v15, v71, 0x3e38aa3b, v131
	v_max_f32_e32 v14, v12, v68
	v_max_f32_e32 v48, v15, v49
	v_max3_f32 v54, v50, v14, v48
	v_fmamk_f32 v48, v56, 0x3e38aa3b, v132
	v_fmamk_f32 v53, v57, 0x3e38aa3b, v133
	v_fmamk_f32 v14, v72, 0x3e38aa3b, v134
	v_fmamk_f32 v51, v73, 0x3e38aa3b, v135
	v_max_f32_e32 v50, v14, v48
	v_max_f32_e32 v52, v51, v53
	v_max3_f32 v64, v54, v50, v52
	v_fmamk_f32 v52, v58, 0x3e38aa3b, v136
	v_fmamk_f32 v57, v59, 0x3e38aa3b, v137
	v_fmamk_f32 v50, v74, 0x3e38aa3b, v138
	v_fmamk_f32 v55, v75, 0x3e38aa3b, v139
	v_max_f32_e32 v54, v50, v52
	v_max_f32_e32 v56, v55, v57
	v_max3_f32 v66, v64, v54, v56
	v_fmamk_f32 v54, v76, 0x3e38aa3b, v140
	v_fmamk_f32 v59, v77, 0x3e38aa3b, v141
	v_fmamk_f32 v56, v60, 0x3e38aa3b, v142
	v_fmamk_f32 v65, v61, 0x3e38aa3b, v143
	v_max_f32_e32 v58, v54, v56
	v_max_f32_e32 v60, v59, v65
	v_max3_f32 v64, v66, v58, v60
	v_fmamk_f32 v58, v78, 0x3e38aa3b, v144
	v_fmamk_f32 v60, v62, 0x3e38aa3b, v146
	v_fmamk_f32 v61, v79, 0x3e38aa3b, v145
	v_fmamk_f32 v67, v63, 0x3e38aa3b, v147
	v_max_f32_e32 v62, v58, v60
	v_max_f32_e32 v63, v61, v67
	v_max3_f32 v62, v64, v62, v63
	v_add_f32_e32 v63, 0x41000000, v102
	v_cmp_gt_f32_e32 vcc, v62, v63
	s_cbranch_vccz .LBB0_288
	v_xor_b32_e32 v63, 32, v223
	v_cmp_lt_i32_e32 vcc, v63, v225
	s_nop 1
	v_cndmask_b32_e32 v63, v223, v63, vcc
	v_lshlrev_b32_e32 v63, 2, v63
	ds_bpermute_b32 v63, v63, v62
	s_waitcnt lgkmcnt(0)
	v_max3_f32 v63, v102, v62, v63
	v_sub_f32_e32 v62, v102, v63
	v_exp_f32_e32 v62, v62
	v_mov_b32_e32 v102, v63
	v_mul_f32_e32 v112, v112, v62
	v_pk_mul_f32 v[46:47], v[46:47], v[62:63] op_sel_hi:[1,0]
	v_pk_mul_f32 v[44:45], v[44:45], v[62:63] op_sel_hi:[1,0]
	v_pk_mul_f32 v[42:43], v[42:43], v[62:63] op_sel_hi:[1,0]
	v_pk_mul_f32 v[40:41], v[40:41], v[62:63] op_sel_hi:[1,0]
	v_pk_mul_f32 v[38:39], v[38:39], v[62:63] op_sel_hi:[1,0]
	v_pk_mul_f32 v[36:37], v[36:37], v[62:63] op_sel_hi:[1,0]
	v_pk_mul_f32 v[34:35], v[34:35], v[62:63] op_sel_hi:[1,0]
	v_pk_mul_f32 v[32:33], v[32:33], v[62:63] op_sel_hi:[1,0]
	v_pk_mul_f32 v[30:31], v[30:31], v[62:63] op_sel_hi:[1,0]
	v_pk_mul_f32 v[28:29], v[28:29], v[62:63] op_sel_hi:[1,0]
	v_pk_mul_f32 v[26:27], v[26:27], v[62:63] op_sel_hi:[1,0]
	v_pk_mul_f32 v[24:25], v[24:25], v[62:63] op_sel_hi:[1,0]
	v_pk_mul_f32 v[22:23], v[22:23], v[62:63] op_sel_hi:[1,0]
	v_pk_mul_f32 v[20:21], v[20:21], v[62:63] op_sel_hi:[1,0]
	v_pk_mul_f32 v[18:19], v[18:19], v[62:63] op_sel_hi:[1,0]
	v_pk_mul_f32 v[16:17], v[16:17], v[62:63] op_sel_hi:[1,0]

; DI float bflo(unsigned u) { return __uint_as_float(u << 16); }
; template <int MODE, int NQ, int TS, bool FAST = false> ...
;     ...
;   bf16x8 qf[NQ][4];
; #pragma unroll
;   for (int nq = 0; nq < NQ; ++nq) { const bf16_t* qp = proj + (size_t)(seq_base + TS * (q0w + 32 * nq + r32)) * ld + qoff + hh * 8;
; #pragma unroll
;     for (int ks = 0; ks < 4; ++ks) qf[nq][ks] = *(const bf16x8*)(qp + ks * 16); }
;   f32x16 o[NQ][2];
;   float m2[NQ], l[NQ];
; #pragma unroll
;   for (int nq = 0; nq < NQ; ++nq) {
;     if (MODE == 0) {
;       const size_t tok = (size_t)(seq_base + q0w + 32 * nq + r32);
;       const bf16_t* po = part_o + tok * 512 + ooff + 4 * hh; const float* pm = part_ml + (tok * 8 + (ooff >> 6)) * 2;
;       m2[nq] = pm[0]; l[nq] = hh ? 0.f : pm[1];
; #pragma unroll
;       for (int g = 0; g < 4; ++g) { const uint2 a = *(const uint2*)(po + 8 * g), b = *(const uint2*)(po + 32 + 8 * g);
;         o[nq][0][4 * g] = bflo(a.x); o[nq][0][4 * g + 1] = bfhi(a.x); o[nq][0][4 * g + 2] = bflo(a.y); o[nq][0][4 * g + 3] = bfhi(a.y);
;         o[nq][1][4 * g] = bflo(b.x); o[nq][1][4 * g + 1] = bfhi(b.x); o[nq][1][4 * g + 2] = bflo(b.y); o[nq][1][4 * g + 3] = bfhi(b.y); }
;     } else {
;       m2[nq] = (MODE == 2) ? sink2 : -1e30f; l[nq] = 0.f;
; #pragma unroll
;       for (int r = 0; r < 16; ++r) { o[nq][0][r] = 0.f; o[nq][1][r] = 0.f; }
;     }
;   }
;   PG8_LAS unsigned char* L = (PG8_LAS unsigned char*)lds;
;   const int kkey_ = wave * 8 + (lane >> 3);
;   const bf16_t* kg = proj + (size_t)(seq_base + TS * kkey_) * ld + koff + (((lane & 7) ^ ((kkey_ >> 1) & 7)) * 8);
;   const bf16_t* vg = proj + (size_t)(seq_base + TS * ((wave & 3) * 16 + (lane >> 2))) * ld + voff + ((wave >> 2) * 4 + (lane & 3)) * 8;
;   const unsigned sdst = (unsigned)__builtin_amdgcn_readfirstlane(wave * 1024);
;     ...
;   const int ktl = kt1 - 1;
;   constexpr int TAB_OFF = 6 * 16384, TAB_N = (MODE == 3) ? 640 : 1024, TAB_ZERO = TAB_N / 2;
;   if (MODE == 0 || MODE == 3) {
;     float* tab = (float*)(lds + TAB_OFF);
;     for (int e = tid; e < TAB_N; e += 512) {
;       const int oo = e - TAB_ZERO, aa = oo < 0 ? -oo : oo;
;       if (MODE == 0) {
;         const int c = (aa <= 64 ? 1 : 0) + (((oo & 3) == 0 && aa <= 256) ? 1 : 0) + (((oo & 15) == 0 && aa <= 256) ? 1 : 0);
;         tab[e] = c ? (-slope2 * (float)aa + (c == 1 ? 0.f : (c == 2 ? 1.f : 1.5849625007f))) : -1e30f;
;       } else {
.LBB0_421:
	s_lshl_b32 s0, s4, 7
	v_lshl_or_b32 v0, s8, 8, v240
	s_add_i32 s0, s6, s0
	v_lshlrev_b32_e32 v0, 1, v0
	s_lshl_b32 s7, s8, 6
	v_add_u32_e32 v37, s0, v239
	v_lshl_add_u64 v[38:39], s[66:67], 0, v[0:1]
	s_and_saveexec_b64 s[0:1], s[36:37]
	s_xor_b64 s[0:1], exec, s[0:1]
	s_cbranch_execz .LBB0_434
	v_mov_b32_e32 v8, v222
	v_mov_b32_e32 v3, v1
	v_and_b32_e32 v9, 31, v8
	v_bfe_u32 v242, v8, 5, 1
	v_add_u32_e32 v168, v9, v37
	v_lshlrev_b32_e32 v2, 4, v242
	v_lshl_add_u64 v[2:3], v[38:39], 0, v[2:3]
	s_movk_i32 s4, 0x1200
	v_add_u32_e32 v166, 32, v168
	v_mad_i64_i32 v[4:5], s[8:9], v168, s4, v[2:3]
	v_mad_i64_i32 v[2:3], s[8:9], v166, s4, v[2:3]
	global_load_dwordx4 v[130:133], v[4:5], off offset:3072
	global_load_dwordx4 v[134:137], v[4:5], off offset:3104
	global_load_dwordx4 v[138:141], v[4:5], off offset:3136
	global_load_dwordx4 v[142:145], v[4:5], off offset:3168
	global_load_dwordx4 v[146:149], v[2:3], off offset:3072
	global_load_dwordx4 v[150:153], v[2:3], off offset:3104
	global_load_dwordx4 v[154:157], v[2:3], off offset:3136
	global_load_dwordx4 v[158:161], v[2:3], off offset:3168
	v_ashrrev_i32_e32 v10, 6, v8
	v_bfe_u32 v2, v8, 3, 3
	v_lshl_or_b32 v4, v10, 3, v2
	v_add_u32_e32 v5, s6, v4
	v_lshrrev_b32_e32 v4, 1, v4
	v_mov_b64_e32 v[2:3], s[66:67]
	v_xor_b32_e32 v4, v4, v8
	v_mad_i64_i32 v[2:3], s[8:9], v5, s4, v[2:3]
	s_lshl_b32 s76, s7, 1
	v_lshlrev_b32_e32 v4, 4, v4
	v_lshl_add_u64 v[2:3], v[2:3], 0, s[76:77]
	v_and_b32_e32 v4, 0x70, v4
	v_mov_b32_e32 v5, v1
	v_lshl_add_u64 v[2:3], v[2:3], 0, v[4:5]
	v_lshlrev_b32_e32 v4, 4, v10
	v_and_b32_e32 v4, 48, v4
	v_bfe_u32 v5, v8, 2, 4
	v_add3_u32 v4, v5, s6, v4
	v_and_b32_e32 v11, 3, v8
	s_mov_b32 s4, 0x1ffffffc
	v_mul_i32_i24_e32 v4, 0x900, v4
	v_mov_b32_e32 v5, v1
	v_and_or_b32 v6, v10, s4, v11
	v_lshl_add_u64 v[4:5], v[4:5], 1, s[66:67]
	v_lshlrev_b32_e32 v6, 3, v6
	v_readfirstlane_b32 s4, v10
	s_mov_b64 s[8:9], 0x1000
	v_lshl_add_u64 v[4:5], v[4:5], 0, s[76:77]
	v_ashrrev_i32_e32 v7, 31, v6
	s_lshl_b32 s4, s4, 10
	v_lshl_add_u64 v[172:173], v[2:3], 0, s[8:9]
	v_lshl_add_u64 v[4:5], v[6:7], 1, v[4:5]
	s_mov_b64 s[8:9], 0x1100
	s_mov_b32 m0, s4
	v_lshl_add_u64 v[174:175], v[4:5], 0, s[8:9]
	global_load_lds_dwordx4 v[172:173], off
	s_add_i32 m0, s4, 0x2000
	s_mov_b64 s[8:9], 0x49000
	global_load_lds_dwordx4 v[174:175], off
	v_lshl_add_u64 v[6:7], v[2:3], 0, s[8:9]
	s_add_i32 m0, s4, 0x4000
	s_mov_b64 s[8:9], 0x49100
	global_load_lds_dwordx4 v[6:7], off
	v_lshl_add_u64 v[6:7], v[4:5], 0, s[8:9]
	s_add_i32 m0, s4, 0x6000
	s_mov_b64 s[8:9], 0x91000
	global_load_lds_dwordx4 v[6:7], off
	v_lshl_add_u64 v[6:7], v[2:3], 0, s[8:9]
	s_add_i32 m0, s4, 0x8000
	s_mov_b64 s[8:9], 0x91100
	global_load_lds_dwordx4 v[6:7], off
	v_lshl_add_u64 v[6:7], v[4:5], 0, s[8:9]
	s_add_i32 m0, s4, 0xa000
	s_mov_b64 s[8:9], 0xd9000
	global_load_lds_dwordx4 v[6:7], off
	v_lshl_add_u64 v[2:3], v[2:3], 0, s[8:9]
	s_add_i32 m0, s4, 0xc000
	s_mov_b64 s[8:9], 0xd9100
	global_load_lds_dwordx4 v[2:3], off
	v_lshl_add_u64 v[2:3], v[4:5], 0, s[8:9]
	s_add_i32 m0, s4, 0xe000
	v_bfe_u32 v4, v8, 1, 3
	global_load_lds_dwordx4 v[2:3], off
	v_lshrrev_b32_e32 v3, 1, v8
	v_lshlrev_b32_e32 v2, 7, v9
	v_bitop3_b32 v3, v242, v3, 7 bitop3:0x78
	v_lshl_or_b32 v243, v3, 4, v2
	v_bitop3_b32 v3, v242, v4, 2 bitop3:0x36
	v_lshl_or_b32 v244, v3, 4, v2
	v_bitop3_b32 v3, v242, v4, 4 bitop3:0x36
	v_lshl_or_b32 v246, v3, 4, v2
	v_bitop3_b32 v3, v242, v4, 6 bitop3:0x36
	v_lshl_or_b32 v247, v3, 4, v2
	v_lshlrev_b32_e32 v2, 4, v8
	v_and_b32_e32 v2, 0xc0, v2
	v_lshlrev_b32_e32 v3, 1, v8
	s_waitcnt vmcnt(6) lgkmcnt(0)
	s_barrier
	v_lshl_or_b32 v2, v242, 8, v2
	v_and_b32_e32 v3, 32, v3
	v_lshlrev_b32_e32 v4, 3, v11
	v_mov_b32_e32 v50, v1
	v_mov_b32_e32 v51, v1
	v_or3_b32 v245, v2, v3, v4
	v_cmp_lt_i32_e32 vcc, 3, v10
	v_cmp_gt_i32_e64 s[38:39], 4, v10
	v_mov_b32_e32 v52, v1
	v_mov_b32_e32 v53, v1
	v_mov_b32_e32 v54, v1
	v_mov_b32_e32 v55, v1
	v_mov_b32_e32 v56, v1
	v_mov_b32_e32 v57, v1
	v_mov_b32_e32 v58, v1
	v_mov_b32_e32 v59, v1
	v_mov_b32_e32 v60, v1
	v_mov_b32_e32 v61, v1
	v_mov_b32_e32 v62, v1
	v_mov_b32_e32 v63, v1
	v_mov_b32_e32 v64, v1
	v_mov_b32_e32 v65, v1
	v_mov_b32_e32 v170, 0
	v_mov_b64_e32 v[34:35], v[50:51]
	v_mov_b64_e32 v[18:19], v[50:51]
	v_mov_b64_e32 v[2:3], v[50:51]
	s_movk_i32 s22, 0x1200
	v_ashrrev_i32_e32 v169, 31, v168
	v_ashrrev_i32_e32 v167, 31, v166
	s_add_i32 s8, s5, -1
	s_mov_b32 s14, 0
	v_mov_b64_e32 v[36:37], v[52:53]
	v_mov_b64_e32 v[38:39], v[54:55]
	v_mov_b64_e32 v[40:41], v[56:57]
	v_mov_b64_e32 v[42:43], v[58:59]
	v_mov_b64_e32 v[44:45], v[60:61]
	v_mov_b64_e32 v[46:47], v[62:63]
	v_mov_b64_e32 v[48:49], v[64:65]
	v_mov_b64_e32 v[20:21], v[52:53]
	v_mov_b64_e32 v[22:23], v[54:55]
	v_mov_b64_e32 v[24:25], v[56:57]
	v_mov_b64_e32 v[26:27], v[58:59]
	v_mov_b64_e32 v[28:29], v[60:61]
	v_mov_b64_e32 v[30:31], v[62:63]
	v_mov_b64_e32 v[32:33], v[64:65]
	v_mov_b64_e32 v[4:5], v[52:53]
	v_mov_b64_e32 v[6:7], v[54:55]
	v_mov_b64_e32 v[8:9], v[56:57]
	v_mov_b64_e32 v[10:11], v[58:59]
	v_mov_b64_e32 v[12:13], v[60:61]
	v_mov_b64_e32 v[14:15], v[62:63]
	v_mov_b64_e32 v[16:17], v[64:65]
	s_mov_b32 s13, 0
	s_mov_b32 s9, 0
	v_mov_b32_e32 v171, v170
; #define MFMA32(a, b, c) __builtin_amdgcn_mfma_f32_32x32x16_bf16((a), (b), (c), 0, 0, 0)
; DI unsigned pack2(float lo, float hi) { f32x2_t v = {lo, hi}; return __builtin_bit_cast(unsigned, __builtin_convertvector(v, bf16x2_t)); }
; template <int MODE, int NQ, int TS, bool FAST = false> ...
;     ...
;   auto QK = [&](int slot) {
;     const char* kb_ = lds + slot * 16384;
; #pragma unroll
;     for (int nq = 0; nq < NQ; ++nq)
; #pragma unroll
;       for (int r = 0; r < 16; ++r) { s[nq][0][r] = 0.f; s[nq][1][r] = 0.f; }
; #pragma unroll
;     for (int ks = 0; ks < 4; ++ks) {
;       const bf16x8 k0 = *(const bf16x8*)(kb_ + kfo4[ks]), k1 = *(const bf16x8*)(kb_ + kfo4[ks] + 4096);
; #pragma unroll
;       for (int nq = 0; nq < NQ; ++nq) { s[nq][0] = MFMA32(k0, qf[nq][ks], s[nq][0]); s[nq][1] = MFMA32(k1, qf[nq][ks], s[nq][1]); }
;     }
;     ...
;       float ls = 0.f;
; #pragma unroll
;       for (int r = 0; r < 16; ++r) {
;         float pa, pb;
;         if (MODE == 1) {
;           if (FAST) { pa = __builtin_amdgcn_exp2f(s0[r]); pb = __builtin_amdgcn_exp2f(s1[r]); }
;           else { pa = __builtin_amdgcn_exp2f(s0[r] - mn); pb = __builtin_amdgcn_exp2f(s1[r] - mn); }
;         }
;         else { pa = __builtin_amdgcn_exp2f(s0[r] - mn); pb = __builtin_amdgcn_exp2f(s1[r] - mn); }
;         s0[r] = pa; s1[r] = pb; ls += pa + pb;
;       }
;       l[nq] += ls;
; #pragma unroll
;       for (int ks = 0; ks < 4; ++ks) {
;         uint4 t4;
;         const int rb = 8 * (ks & 1);
;         if (ks < 2) { t4.x = pack2(s0[rb], s0[rb + 1]); t4.y = pack2(s0[rb + 2], s0[rb + 3]); t4.z = pack2(s0[rb + 4], s0[rb + 5]); t4.w = pack2(s0[rb + 6], s0[rb + 7]); }
;         else { t4.x = pack2(s1[rb], s1[rb + 1]); t4.y = pack2(s1[rb + 2], s1[rb + 3]); t4.z = pack2(s1[rb + 4], s1[rb + 5]); t4.w = pack2(s1[rb + 6], s1[rb + 7]); }
;         pf[nq][ks] = __builtin_bit_cast(bf16x8, t4);
;       }
.LBB0_423:
	s_mov_b32 s12, s14
	s_add_i32 s14, s9, 4
	s_min_i32 s16, s14, s8
	s_cmp_gt_i32 s12, 1
	s_cselect_b32 s14, -2, 4
	s_add_i32 s18, s14, s12
	v_mad_i64_i32 v[82:83], s[14:15], s16, v237, v[172:173]
	s_lshl_b32 s14, s18, 14
	s_add_i32 s18, s4, s14
	s_mov_b32 m0, s18
	s_nop 0
	global_load_lds_dwordx4 v[82:83], off
	v_mad_i64_i32 v[82:83], s[14:15], s16, v237, v[174:175]
	s_add_i32 m0, s18, 0x2000
	s_nop 0
	global_load_lds_dwordx4 v[82:83], off
	s_and_saveexec_b64 s[14:15], s[38:39]
	s_xor_b64 s[26:27], exec, s[14:15]
	s_cbranch_execz .LBB0_425
	s_lshl_b32 s14, s12, 14
	v_or_b32_e32 v70, s14, v243
	ds_read_b128 v[66:69], v70
	ds_read_b128 v[70:73], v70 offset:4096
	v_or_b32_e32 v180, s14, v244
	ds_read_b128 v[176:179], v180
	ds_read_b128 v[180:183], v180 offset:4096
	s_waitcnt lgkmcnt(0)
	v_mfma_f32_32x32x16_bf16 v[114:129], v[66:69], v[130:133], 0
	v_mfma_f32_32x32x16_bf16 v[98:113], v[70:73], v[130:133], 0
	v_mfma_f32_32x32x16_bf16 v[82:97], v[66:69], v[146:149], 0
	v_mfma_f32_32x32x16_bf16 v[66:81], v[70:73], v[146:149], 0
	v_mfma_f32_32x32x16_bf16 v[98:113], v[180:183], v[134:137], v[98:113]
	v_mfma_f32_32x32x16_bf16 v[114:129], v[176:179], v[134:137], v[114:129]
	v_mfma_f32_32x32x16_bf16 v[66:81], v[180:183], v[150:153], v[66:81]
	v_or_b32_e32 v180, s14, v246
	v_mfma_f32_32x32x16_bf16 v[82:97], v[176:179], v[150:153], v[82:97]
	ds_read_b128 v[176:179], v180
	ds_read_b128 v[180:183], v180 offset:4096
	s_waitcnt lgkmcnt(0)
	v_mfma_f32_32x32x16_bf16 v[98:113], v[180:183], v[138:141], v[98:113]
	v_mfma_f32_32x32x16_bf16 v[114:129], v[176:179], v[138:141], v[114:129]
	v_mfma_f32_32x32x16_bf16 v[66:81], v[180:183], v[154:157], v[66:81]
	v_or_b32_e32 v180, s14, v247
	v_mfma_f32_32x32x16_bf16 v[82:97], v[176:179], v[154:157], v[82:97]
	ds_read_b128 v[176:179], v180
	ds_read_b128 v[180:183], v180 offset:4096
	s_waitcnt lgkmcnt(0)
	v_mfma_f32_32x32x16_bf16 v[98:113], v[180:183], v[142:145], v[98:113]
	v_mfma_f32_32x32x16_bf16 v[114:129], v[176:179], v[142:145], v[114:129]
	s_nop 10
	v_sub_f32_e32 v98, v98, v165
	v_mfma_f32_32x32x16_bf16 v[66:81], v[180:183], v[158:161], v[66:81]
	v_sub_f32_e32 v114, v114, v165
	v_mfma_f32_32x32x16_bf16 v[82:97], v[176:179], v[158:161], v[82:97]
	v_exp_f32_e32 v179, v98
	v_sub_f32_e32 v98, v115, v165
	v_exp_f32_e32 v115, v98
	v_sub_f32_e32 v98, v99, v165
	v_exp_f32_e32 v181, v98
	v_sub_f32_e32 v98, v116, v165
	s_nop 3
	v_sub_f32_e32 v66, v66, v165
	v_exp_f32_e32 v183, v98
	v_sub_f32_e32 v98, v100, v165
	v_exp_f32_e32 v178, v66
	v_sub_f32_e32 v66, v83, v165
	v_exp_f32_e32 v177, v114
	v_exp_f32_e32 v185, v98
	v_sub_f32_e32 v98, v117, v165
	v_exp_f32_e32 v114, v66
	v_sub_f32_e32 v66, v67, v165
	v_exp_f32_e32 v117, v98
	v_sub_f32_e32 v98, v101, v165
	v_exp_f32_e32 v180, v66
	v_sub_f32_e32 v66, v84, v165
	v_exp_f32_e32 v187, v98
	v_sub_f32_e32 v98, v118, v165
	v_exp_f32_e32 v182, v66
	v_sub_f32_e32 v66, v68, v165
	v_exp_f32_e32 v189, v98
	v_sub_f32_e32 v98, v102, v165
	v_exp_f32_e32 v184, v66
	v_sub_f32_e32 v66, v85, v165
	v_exp_f32_e32 v191, v98
	v_sub_f32_e32 v98, v119, v165
	v_exp_f32_e32 v116, v66
	v_sub_f32_e32 v66, v69, v165
	v_exp_f32_e32 v119, v98
	v_sub_f32_e32 v98, v103, v165
	v_exp_f32_e32 v186, v66
	v_sub_f32_e32 v66, v86, v165
	v_exp_f32_e32 v193, v98
	v_sub_f32_e32 v98, v120, v165
	v_exp_f32_e32 v188, v66
	v_sub_f32_e32 v66, v70, v165
	v_sub_f32_e32 v70, v88, v165
	v_exp_f32_e32 v195, v98
	v_sub_f32_e32 v98, v104, v165
	v_exp_f32_e32 v194, v70
	v_sub_f32_e32 v70, v72, v165
	v_exp_f32_e32 v197, v98
	v_sub_f32_e32 v98, v121, v165
	v_exp_f32_e32 v196, v70
	v_sub_f32_e32 v70, v89, v165
	v_exp_f32_e32 v121, v98
	v_sub_f32_e32 v98, v105, v165
	v_exp_f32_e32 v120, v70
	v_sub_f32_e32 v70, v73, v165
	v_exp_f32_e32 v199, v98
	v_sub_f32_e32 v98, v122, v165
	v_sub_f32_e32 v82, v82, v165
	v_exp_f32_e32 v198, v70
	v_sub_f32_e32 v70, v90, v165
	v_exp_f32_e32 v201, v98
	v_sub_f32_e32 v98, v106, v165
	v_exp_f32_e32 v176, v82
	v_exp_f32_e32 v200, v70
	v_sub_f32_e32 v70, v74, v165
	v_exp_f32_e32 v203, v98
	v_sub_f32_e32 v98, v123, v165
	v_exp_f32_e32 v202, v70
	v_sub_f32_e32 v70, v91, v165
	v_exp_f32_e32 v123, v98
	v_sub_f32_e32 v98, v107, v165
	v_exp_f32_e32 v122, v70
	v_sub_f32_e32 v70, v75, v165
	v_exp_f32_e32 v205, v98
	v_sub_f32_e32 v98, v124, v165
	v_exp_f32_e32 v204, v70
	v_sub_f32_e32 v70, v92, v165
	v_exp_f32_e32 v207, v98
	v_sub_f32_e32 v98, v108, v165
	v_exp_f32_e32 v190, v66
	v_pk_add_f32 v[66:67], v[176:177], v[178:179]
	v_exp_f32_e32 v206, v70
	v_sub_f32_e32 v70, v76, v165
	v_exp_f32_e32 v209, v98
	v_sub_f32_e32 v98, v125, v165
	v_pk_add_f32 v[66:67], v[66:67], 0 op_sel_hi:[1,0]
	v_pk_add_f32 v[68:69], v[114:115], v[180:181]
	v_exp_f32_e32 v208, v70
	v_sub_f32_e32 v70, v93, v165
	v_exp_f32_e32 v125, v98
	v_sub_f32_e32 v98, v109, v165
	v_pk_add_f32 v[66:67], v[68:69], v[66:67]
	v_pk_add_f32 v[68:69], v[182:183], v[184:185]
	v_exp_f32_e32 v124, v70
	v_sub_f32_e32 v70, v77, v165
	v_exp_f32_e32 v211, v98
	v_sub_f32_e32 v98, v126, v165
	v_pk_add_f32 v[66:67], v[68:69], v[66:67]
	v_pk_add_f32 v[68:69], v[116:117], v[186:187]
	v_exp_f32_e32 v210, v70
	v_sub_f32_e32 v70, v94, v165
	v_exp_f32_e32 v213, v98
	v_sub_f32_e32 v98, v110, v165
	v_pk_add_f32 v[66:67], v[68:69], v[66:67]
	v_pk_add_f32 v[68:69], v[188:189], v[190:191]
	v_exp_f32_e32 v212, v70
	v_sub_f32_e32 v70, v78, v165
	v_exp_f32_e32 v215, v98
	v_sub_f32_e32 v98, v127, v165
	v_pk_add_f32 v[66:67], v[68:69], v[66:67]
	v_sub_f32_e32 v68, v87, v165
	v_exp_f32_e32 v214, v70
	v_sub_f32_e32 v70, v95, v165
	v_or_b32_e32 v92, s14, v245
	v_exp_f32_e32 v127, v98
	v_sub_f32_e32 v98, v111, v165
	v_exp_f32_e32 v118, v68
	v_exp_f32_e32 v126, v70
	v_sub_f32_e32 v70, v79, v165
	ds_read_b64_tr_b16 v[84:85], v92 offset:8192
	ds_read_b64_tr_b16 v[86:87], v92 offset:8704
	ds_read_b64_tr_b16 v[88:89], v92 offset:12288
	ds_read_b64_tr_b16 v[90:91], v92 offset:12800
	v_exp_f32_e32 v217, v98
	v_sub_f32_e32 v98, v128, v165
	v_exp_f32_e32 v216, v70
	v_sub_f32_e32 v70, v96, v165
	v_exp_f32_e32 v219, v98
	v_sub_f32_e32 v98, v112, v165
	v_exp_f32_e32 v218, v70
	v_sub_f32_e32 v70, v80, v165
	v_exp_f32_e32 v221, v98
	v_sub_f32_e32 v98, v129, v165
	v_exp_f32_e32 v220, v70
	v_sub_f32_e32 v70, v97, v165
	v_exp_f32_e32 v129, v98
	v_sub_f32_e32 v98, v113, v165
	v_cvt_pk_bf16_f32 v110, v177, v115
	v_cvt_pk_bf16_f32 v111, v183, v117
	v_cvt_pk_bf16_f32 v112, v189, v119
	v_cvt_pk_bf16_f32 v113, v195, v121
	v_exp_f32_e32 v128, v70
	v_sub_f32_e32 v70, v81, v165
	v_cvt_pk_bf16_f32 v78, v176, v114
	v_cvt_pk_bf16_f32 v79, v182, v116
	v_cvt_pk_bf16_f32 v80, v188, v118
	v_cvt_pk_bf16_f32 v81, v194, v120
	s_waitcnt lgkmcnt(0)
; #define MFMA32(a, b, c) __builtin_amdgcn_mfma_f32_32x32x16_bf16((a), (b), (c), 0, 0, 0)
; DI unsigned pack2(float lo, float hi) { f32x2_t v = {lo, hi}; return __builtin_bit_cast(unsigned, __builtin_convertvector(v, bf16x2_t)); }
; DI s16x4 vtr(const char* p) { return __builtin_amdgcn_ds_read_tr16_b64_v4i16((lds_s16x4_ptr)p); }
; template <int MODE, int NQ, int TS, bool FAST = false> ...
;     ...
;       float ls = 0.f;
; #pragma unroll
;       for (int r = 0; r < 16; ++r) {
;         float pa, pb;
;         if (MODE == 1) {
;           if (FAST) { pa = __builtin_amdgcn_exp2f(s0[r]); pb = __builtin_amdgcn_exp2f(s1[r]); }
;           else { pa = __builtin_amdgcn_exp2f(s0[r] - mn); pb = __builtin_amdgcn_exp2f(s1[r] - mn); }
;         }
;         else { pa = __builtin_amdgcn_exp2f(s0[r] - mn); pb = __builtin_amdgcn_exp2f(s1[r] - mn); }
;         s0[r] = pa; s1[r] = pb; ls += pa + pb;
;       }
;       l[nq] += ls;
; #pragma unroll
;       for (int ks = 0; ks < 4; ++ks) {
;         uint4 t4;
;         const int rb = 8 * (ks & 1);
;         if (ks < 2) { t4.x = pack2(s0[rb], s0[rb + 1]); t4.y = pack2(s0[rb + 2], s0[rb + 3]); t4.z = pack2(s0[rb + 4], s0[rb + 5]); t4.w = pack2(s0[rb + 6], s0[rb + 7]); }
;         else { t4.x = pack2(s1[rb], s1[rb + 1]); t4.y = pack2(s1[rb + 2], s1[rb + 3]); t4.z = pack2(s1[rb + 4], s1[rb + 5]); t4.w = pack2(s1[rb + 6], s1[rb + 7]); }
;         pf[nq][ks] = __builtin_bit_cast(bf16x8, t4);
;       }
;     }
;   };
;   auto PV = [&](int slot) {
;     const char* vb_ = lds + slot * 16384 + vfo;
; #pragma unroll
;     for (int ks = 0; ks < 4; ++ks) {
;       const s16x4 a0 = vtr(vb_ + ks * 1024), a1 = vtr(vb_ + ks * 1024 + 512);
;       const s16x4 b0 = vtr(vb_ + 4096 + ks * 1024), b1 = vtr(vb_ + 4096 + ks * 1024 + 512);
;       const bf16x8 v0 = __builtin_shufflevector(a0, a1, 0, 1, 2, 3, 4, 5, 6, 7);
;       const bf16x8 v1 = __builtin_shufflevector(b0, b1, 0, 1, 2, 3, 4, 5, 6, 7);
; #pragma unroll
;       for (int nq = 0; nq < NQ; ++nq) { o[nq][0] = MFMA32(v0, pf[nq][ks], o[nq][0]); o[nq][1] = MFMA32(v1, pf[nq][ks], o[nq][1]); }
;     }
	v_mfma_f32_32x32x16_bf16 v[50:65], v[84:87], v[110:113], v[50:65]
	v_cvt_pk_bf16_f32 v102, v201, v123
	v_cvt_pk_bf16_f32 v103, v207, v125
	v_cvt_pk_bf16_f32 v104, v213, v127
	v_cvt_pk_bf16_f32 v105, v219, v129
	v_sub_f32_e32 v68, v71, v165
	v_cvt_pk_bf16_f32 v74, v200, v122
	v_cvt_pk_bf16_f32 v75, v206, v124
	v_mfma_f32_32x32x16_bf16 v[34:49], v[88:91], v[110:113], v[34:49]
	v_cvt_pk_bf16_f32 v76, v212, v126
	v_cvt_pk_bf16_f32 v77, v218, v128
	v_exp_f32_e32 v192, v68
	v_cvt_pk_bf16_f32 v106, v179, v181
	v_cvt_pk_bf16_f32 v107, v185, v187
	v_cvt_pk_bf16_f32 v108, v191, v193
	v_pk_add_f32 v[68:69], v[118:119], v[192:193]
	v_mfma_f32_32x32x16_bf16 v[18:33], v[84:87], v[78:81], v[18:33]
	v_add_f32_e64 v66, v68, v66
	v_add_f32_e64 v67, v69, v67
	v_add_f32_e64 v68, v194, v196
	v_add_f32_e64 v69, v195, v197
	v_cvt_pk_bf16_f32 v109, v197, v199
	v_pk_add_f32 v[66:67], v[68:69], v[66:67]
	v_pk_add_f32 v[68:69], v[120:121], v[198:199]
	v_exp_f32_e32 v226, v70
	v_pk_add_f32 v[66:67], v[68:69], v[66:67]
	v_mfma_f32_32x32x16_bf16 v[2:17], v[88:91], v[78:81], v[2:17]
	ds_read_b64_tr_b16 v[84:85], v92 offset:9216
	ds_read_b64_tr_b16 v[86:87], v92 offset:9728
	ds_read_b64_tr_b16 v[88:89], v92 offset:13312
	ds_read_b64_tr_b16 v[90:91], v92 offset:13824
	v_add_f32_e64 v68, v200, v202
	v_add_f32_e64 v69, v201, v203
	v_cvt_pk_bf16_f32 v70, v178, v180
	v_cvt_pk_bf16_f32 v71, v184, v186
	v_cvt_pk_bf16_f32 v72, v190, v192
	v_cvt_pk_bf16_f32 v73, v196, v198
	v_pk_add_f32 v[66:67], v[68:69], v[66:67]
	s_waitcnt lgkmcnt(0)
	v_mfma_f32_32x32x16_bf16 v[50:65], v[84:87], v[102:105], v[50:65]
	v_add_f32_e64 v68, v122, v204
	v_add_f32_e64 v69, v123, v205
	v_exp_f32_e32 v227, v98
	v_pk_add_f32 v[66:67], v[68:69], v[66:67]
	v_pk_add_f32 v[68:69], v[206:207], v[208:209]
	v_cvt_pk_bf16_f32 v98, v203, v205
	v_pk_add_f32 v[66:67], v[68:69], v[66:67]
	v_pk_add_f32 v[68:69], v[124:125], v[210:211]
	v_mfma_f32_32x32x16_bf16 v[34:49], v[88:91], v[102:105], v[34:49]
	v_add_f32_e64 v66, v68, v66
	v_add_f32_e64 v67, v69, v67
	v_add_f32_e64 v68, v212, v214
	v_add_f32_e64 v69, v213, v215
	v_cvt_pk_bf16_f32 v99, v209, v211
	v_pk_add_f32 v[66:67], v[68:69], v[66:67]
	v_pk_add_f32 v[68:69], v[126:127], v[216:217]
	v_cvt_pk_bf16_f32 v100, v215, v217
	v_pk_add_f32 v[66:67], v[68:69], v[66:67]
	v_mfma_f32_32x32x16_bf16 v[18:33], v[84:87], v[74:77], v[18:33]
	v_add_f32_e64 v68, v218, v220
	v_add_f32_e64 v69, v219, v221
	v_cvt_pk_bf16_f32 v101, v221, v227
	v_add_f32_e64 v66, v68, v66
	v_add_f32_e64 v67, v69, v67
	v_pk_add_f32 v[68:69], v[128:129], v[226:227]
	s_nop 0
	v_pk_add_f32 v[82:83], v[68:69], v[66:67]
	v_cvt_pk_bf16_f32 v66, v202, v204
	v_mfma_f32_32x32x16_bf16 v[2:17], v[88:91], v[74:77], v[2:17]
	ds_read_b64_tr_b16 v[84:85], v92 offset:10240
	ds_read_b64_tr_b16 v[86:87], v92 offset:10752
	ds_read_b64_tr_b16 v[88:89], v92 offset:14336
	ds_read_b64_tr_b16 v[90:91], v92 offset:14848
	v_cvt_pk_bf16_f32 v67, v208, v210
	v_cvt_pk_bf16_f32 v68, v214, v216
	v_cvt_pk_bf16_f32 v69, v220, v226
	s_waitcnt lgkmcnt(0)
	v_mfma_f32_32x32x16_bf16 v[50:65], v[84:87], v[106:109], v[50:65]
	v_mfma_f32_32x32x16_bf16 v[34:49], v[88:91], v[106:109], v[34:49]
	v_mfma_f32_32x32x16_bf16 v[18:33], v[84:87], v[70:73], v[18:33]
	v_mfma_f32_32x32x16_bf16 v[2:17], v[88:91], v[70:73], v[2:17]
	ds_read_b64_tr_b16 v[84:85], v92 offset:11264
	ds_read_b64_tr_b16 v[86:87], v92 offset:11776
	ds_read_b64_tr_b16 v[88:89], v92 offset:15360
	ds_read_b64_tr_b16 v[90:91], v92 offset:15872
	s_waitcnt lgkmcnt(0)
	v_mfma_f32_32x32x16_bf16 v[50:65], v[84:87], v[98:101], v[50:65]
	v_mfma_f32_32x32x16_bf16 v[34:49], v[88:91], v[98:101], v[34:49]
	v_mfma_f32_32x32x16_bf16 v[18:33], v[84:87], v[66:69], v[18:33]
	v_mfma_f32_32x32x16_bf16 v[2:17], v[88:91], v[66:69], v[2:17]

; DI float bflo(unsigned u) { return __uint_as_float(u << 16); }
; template <int MODE, int NQ, int TS, bool FAST = false> ...
;     ...
;   bf16x8 qf[NQ][4];
; #pragma unroll
;   for (int nq = 0; nq < NQ; ++nq) { const bf16_t* qp = proj + (size_t)(seq_base + TS * (q0w + 32 * nq + r32)) * ld + qoff + hh * 8;
; #pragma unroll
;     for (int ks = 0; ks < 4; ++ks) qf[nq][ks] = *(const bf16x8*)(qp + ks * 16); }
;   f32x16 o[NQ][2];
;   float m2[NQ], l[NQ];
; #pragma unroll
;   for (int nq = 0; nq < NQ; ++nq) {
;     if (MODE == 0) {
;       const size_t tok = (size_t)(seq_base + q0w + 32 * nq + r32);
;       const bf16_t* po = part_o + tok * 512 + ooff + 4 * hh; const float* pm = part_ml + (tok * 8 + (ooff >> 6)) * 2;
;       m2[nq] = pm[0]; l[nq] = hh ? 0.f : pm[1];
; #pragma unroll
;       for (int g = 0; g < 4; ++g) { const uint2 a = *(const uint2*)(po + 8 * g), b = *(const uint2*)(po + 32 + 8 * g);
;         o[nq][0][4 * g] = bflo(a.x); o[nq][0][4 * g + 1] = bfhi(a.x); o[nq][0][4 * g + 2] = bflo(a.y); o[nq][0][4 * g + 3] = bfhi(a.y);
;         o[nq][1][4 * g] = bflo(b.x); o[nq][1][4 * g + 1] = bfhi(b.x); o[nq][1][4 * g + 2] = bflo(b.y); o[nq][1][4 * g + 3] = bfhi(b.y); }
;     } else {
;       m2[nq] = (MODE == 2) ? sink2 : -1e30f; l[nq] = 0.f;
; #pragma unroll
;       for (int r = 0; r < 16; ++r) { o[nq][0][r] = 0.f; o[nq][1][r] = 0.f; }
;     }
;   }
;   PG8_LAS unsigned char* L = (PG8_LAS unsigned char*)lds;
;   const int kkey_ = wave * 8 + (lane >> 3);
;   const bf16_t* kg = proj + (size_t)(seq_base + TS * kkey_) * ld + koff + (((lane & 7) ^ ((kkey_ >> 1) & 7)) * 8);
;   const bf16_t* vg = proj + (size_t)(seq_base + TS * ((wave & 3) * 16 + (lane >> 2))) * ld + voff + ((wave >> 2) * 4 + (lane & 3)) * 8;
;   const unsigned sdst = (unsigned)__builtin_amdgcn_readfirstlane(wave * 1024);
;     ...
;   const int ktl = kt1 - 1;
;   constexpr int TAB_OFF = 6 * 16384, TAB_N = (MODE == 3) ? 640 : 1024, TAB_ZERO = TAB_N / 2;
;   if (MODE == 0 || MODE == 3) {
;     float* tab = (float*)(lds + TAB_OFF);
;     for (int e = tid; e < TAB_N; e += 512) {
;       const int oo = e - TAB_ZERO, aa = oo < 0 ? -oo : oo;
;       if (MODE == 0) {
;         const int c = (aa <= 64 ? 1 : 0) + (((oo & 3) == 0 && aa <= 256) ? 1 : 0) + (((oo & 15) == 0 && aa <= 256) ? 1 : 0);
;         tab[e] = c ? (-slope2 * (float)aa + (c == 1 ? 0.f : (c == 2 ? 1.f : 1.5849625007f))) : -1e30f;
;       } else {
.LBB0_434:
	s_andn2_saveexec_b64 s[0:1], s[0:1]
	s_cbranch_execz .LBB0_364
	v_mov_b32_e32 v8, v222
	v_mov_b32_e32 v3, v1
	v_and_b32_e32 v9, 31, v8
	v_bfe_u32 v182, v8, 5, 1
	v_add_u32_e32 v168, v9, v37
	v_lshlrev_b32_e32 v2, 4, v182
	v_lshl_add_u64 v[2:3], v[38:39], 0, v[2:3]
	s_movk_i32 s4, 0x1200
	v_add_u32_e32 v166, 32, v168
	v_mad_i64_i32 v[4:5], s[8:9], v168, s4, v[2:3]
	v_mad_i64_i32 v[2:3], s[8:9], v166, s4, v[2:3]
	global_load_dwordx4 v[130:133], v[4:5], off offset:3072
	global_load_dwordx4 v[134:137], v[4:5], off offset:3104
	global_load_dwordx4 v[138:141], v[4:5], off offset:3136
	global_load_dwordx4 v[142:145], v[4:5], off offset:3168
	global_load_dwordx4 v[146:149], v[2:3], off offset:3072
	global_load_dwordx4 v[150:153], v[2:3], off offset:3104
	global_load_dwordx4 v[154:157], v[2:3], off offset:3136
	global_load_dwordx4 v[158:161], v[2:3], off offset:3168
	v_ashrrev_i32_e32 v10, 6, v8
	v_bfe_u32 v2, v8, 3, 3
	v_lshl_or_b32 v4, v10, 3, v2
	v_add_u32_e32 v5, s6, v4
	v_lshrrev_b32_e32 v4, 1, v4
	v_mov_b64_e32 v[2:3], s[66:67]
	v_xor_b32_e32 v4, v4, v8
	v_mad_i64_i32 v[2:3], s[8:9], v5, s4, v[2:3]
	s_lshl_b32 s76, s7, 1
	v_lshlrev_b32_e32 v4, 4, v4
	v_lshl_add_u64 v[2:3], v[2:3], 0, s[76:77]
	v_and_b32_e32 v4, 0x70, v4
	v_mov_b32_e32 v5, v1
	v_lshl_add_u64 v[2:3], v[2:3], 0, v[4:5]
	v_lshlrev_b32_e32 v4, 4, v10
	v_and_b32_e32 v4, 48, v4
	v_bfe_u32 v5, v8, 2, 4
	v_add3_u32 v4, v5, s6, v4
	v_and_b32_e32 v11, 3, v8
	s_mov_b32 s4, 0x1ffffffc
	v_mul_i32_i24_e32 v4, 0x900, v4
	v_mov_b32_e32 v5, v1
	v_and_or_b32 v6, v10, s4, v11
	v_lshl_add_u64 v[4:5], v[4:5], 1, s[66:67]
	v_lshlrev_b32_e32 v6, 3, v6
	v_readfirstlane_b32 s4, v10
	s_mov_b64 s[8:9], 0x1000
	v_lshl_add_u64 v[4:5], v[4:5], 0, s[76:77]
	v_ashrrev_i32_e32 v7, 31, v6
	s_lshl_b32 s4, s4, 10
	v_lshl_add_u64 v[172:173], v[2:3], 0, s[8:9]
	v_lshl_add_u64 v[4:5], v[6:7], 1, v[4:5]
	s_mov_b64 s[6:7], 0x1100
	s_mov_b32 m0, s4
	v_lshl_add_u64 v[174:175], v[4:5], 0, s[6:7]
	global_load_lds_dwordx4 v[172:173], off
	s_add_i32 m0, s4, 0x2000
	s_mov_b64 s[6:7], 0x49000
	global_load_lds_dwordx4 v[174:175], off
	v_lshl_add_u64 v[6:7], v[2:3], 0, s[6:7]
	s_add_i32 m0, s4, 0x4000
	s_mov_b64 s[6:7], 0x49100
	global_load_lds_dwordx4 v[6:7], off
	v_lshl_add_u64 v[6:7], v[4:5], 0, s[6:7]
	s_add_i32 m0, s4, 0x6000
	s_mov_b64 s[6:7], 0x91000
	global_load_lds_dwordx4 v[6:7], off
	v_lshl_add_u64 v[6:7], v[2:3], 0, s[6:7]
	s_add_i32 m0, s4, 0x8000
	s_mov_b64 s[6:7], 0x91100
	global_load_lds_dwordx4 v[6:7], off
	v_lshl_add_u64 v[6:7], v[4:5], 0, s[6:7]
	s_add_i32 m0, s4, 0xa000
	s_mov_b64 s[6:7], 0xd9000
	global_load_lds_dwordx4 v[6:7], off
	v_lshl_add_u64 v[2:3], v[2:3], 0, s[6:7]
	s_add_i32 m0, s4, 0xc000
	s_mov_b64 s[6:7], 0xd9100
	global_load_lds_dwordx4 v[2:3], off
	v_lshl_add_u64 v[2:3], v[4:5], 0, s[6:7]
	s_add_i32 m0, s4, 0xe000
	v_bfe_u32 v4, v8, 1, 3
	global_load_lds_dwordx4 v[2:3], off
	v_lshrrev_b32_e32 v3, 1, v8
	v_lshlrev_b32_e32 v2, 7, v9
	v_bitop3_b32 v3, v182, v3, 7 bitop3:0x78
	v_lshl_or_b32 v183, v3, 4, v2
	v_bitop3_b32 v3, v182, v4, 2 bitop3:0x36
	v_lshl_or_b32 v184, v3, 4, v2
	v_bitop3_b32 v3, v182, v4, 4 bitop3:0x36
	v_lshl_or_b32 v186, v3, 4, v2
	v_bitop3_b32 v3, v182, v4, 6 bitop3:0x36
	v_lshl_or_b32 v187, v3, 4, v2
	v_lshlrev_b32_e32 v2, 4, v8
	v_and_b32_e32 v2, 0xc0, v2
	v_lshlrev_b32_e32 v3, 1, v8
	s_waitcnt vmcnt(6) lgkmcnt(0)
	s_barrier
	v_lshl_or_b32 v2, v182, 8, v2
	v_and_b32_e32 v3, 32, v3
	v_lshlrev_b32_e32 v4, 3, v11
	v_mov_b32_e32 v50, v1
	v_mov_b32_e32 v51, v1
	v_or3_b32 v185, v2, v3, v4
	v_cmp_lt_i32_e32 vcc, 3, v10
	v_cmp_gt_i32_e64 s[38:39], 4, v10
	v_mov_b32_e32 v52, v1
	v_mov_b32_e32 v53, v1
	v_mov_b32_e32 v54, v1
	v_mov_b32_e32 v55, v1
	v_mov_b32_e32 v56, v1
	v_mov_b32_e32 v57, v1
	v_mov_b32_e32 v58, v1
	v_mov_b32_e32 v59, v1
	v_mov_b32_e32 v60, v1
	v_mov_b32_e32 v61, v1
	v_mov_b32_e32 v62, v1
	v_mov_b32_e32 v63, v1
	v_mov_b32_e32 v64, v1
	v_mov_b32_e32 v65, v1
	v_mov_b32_e32 v170, 0
	v_mov_b64_e32 v[34:35], v[50:51]
	v_mov_b64_e32 v[18:19], v[50:51]
	v_mov_b64_e32 v[2:3], v[50:51]
	s_movk_i32 s22, 0x1200
	v_ashrrev_i32_e32 v169, 31, v168
	v_ashrrev_i32_e32 v167, 31, v166
	s_add_i32 s6, s5, -1
	s_mov_b32 s12, 0
	v_mov_b64_e32 v[36:37], v[52:53]
	v_mov_b64_e32 v[38:39], v[54:55]
	v_mov_b64_e32 v[40:41], v[56:57]
	v_mov_b64_e32 v[42:43], v[58:59]
	v_mov_b64_e32 v[44:45], v[60:61]
	v_mov_b64_e32 v[46:47], v[62:63]
	v_mov_b64_e32 v[48:49], v[64:65]
	v_mov_b64_e32 v[20:21], v[52:53]
	v_mov_b64_e32 v[22:23], v[54:55]
	v_mov_b64_e32 v[24:25], v[56:57]
	v_mov_b64_e32 v[26:27], v[58:59]
	v_mov_b64_e32 v[28:29], v[60:61]
	v_mov_b64_e32 v[30:31], v[62:63]
	v_mov_b64_e32 v[32:33], v[64:65]
	v_mov_b64_e32 v[4:5], v[52:53]
	v_mov_b64_e32 v[6:7], v[54:55]
	v_mov_b64_e32 v[8:9], v[56:57]
	v_mov_b64_e32 v[10:11], v[58:59]
	v_mov_b64_e32 v[12:13], v[60:61]
	v_mov_b64_e32 v[14:15], v[62:63]
	v_mov_b64_e32 v[16:17], v[64:65]
	s_mov_b32 s9, 0
	s_mov_b32 s7, 0
	v_mov_b32_e32 v171, v170
; #define MFMA32(a, b, c) __builtin_amdgcn_mfma_f32_32x32x16_bf16((a), (b), (c), 0, 0, 0)
; DI unsigned pack2(float lo, float hi) { f32x2_t v = {lo, hi}; return __builtin_bit_cast(unsigned, __builtin_convertvector(v, bf16x2_t)); }
; template <int MODE, int NQ, int TS, bool FAST = false> ...
;     ...
;   auto QK = [&](int slot) {
;     const char* kb_ = lds + slot * 16384;
; #pragma unroll
;     for (int nq = 0; nq < NQ; ++nq)
; #pragma unroll
;       for (int r = 0; r < 16; ++r) { s[nq][0][r] = 0.f; s[nq][1][r] = 0.f; }
; #pragma unroll
;     for (int ks = 0; ks < 4; ++ks) {
;       const bf16x8 k0 = *(const bf16x8*)(kb_ + kfo4[ks]), k1 = *(const bf16x8*)(kb_ + kfo4[ks] + 4096);
; #pragma unroll
;       for (int nq = 0; nq < NQ; ++nq) { s[nq][0] = MFMA32(k0, qf[nq][ks], s[nq][0]); s[nq][1] = MFMA32(k1, qf[nq][ks], s[nq][1]); }
;     }
;     ...
;       float ls = 0.f;
; #pragma unroll
;       for (int r = 0; r < 16; ++r) {
;         float pa, pb;
;         if (MODE == 1) {
;           if (FAST) { pa = __builtin_amdgcn_exp2f(s0[r]); pb = __builtin_amdgcn_exp2f(s1[r]); }
;           else { pa = __builtin_amdgcn_exp2f(s0[r] - mn); pb = __builtin_amdgcn_exp2f(s1[r] - mn); }
;         }
;         else { pa = __builtin_amdgcn_exp2f(s0[r] - mn); pb = __builtin_amdgcn_exp2f(s1[r] - mn); }
;         s0[r] = pa; s1[r] = pb; ls += pa + pb;
;       }
;       l[nq] += ls;
; #pragma unroll
;       for (int ks = 0; ks < 4; ++ks) {
;         uint4 t4;
;         const int rb = 8 * (ks & 1);
;         if (ks < 2) { t4.x = pack2(s0[rb], s0[rb + 1]); t4.y = pack2(s0[rb + 2], s0[rb + 3]); t4.z = pack2(s0[rb + 4], s0[rb + 5]); t4.w = pack2(s0[rb + 6], s0[rb + 7]); }
;         else { t4.x = pack2(s1[rb], s1[rb + 1]); t4.y = pack2(s1[rb + 2], s1[rb + 3]); t4.z = pack2(s1[rb + 4], s1[rb + 5]); t4.w = pack2(s1[rb + 6], s1[rb + 7]); }
;         pf[nq][ks] = __builtin_bit_cast(bf16x8, t4);
;       }
.LBB0_436:
	s_mov_b32 s8, s12
	s_add_i32 s12, s7, 4
	s_min_i32 s14, s12, s6
	s_cmp_gt_i32 s8, 1
	s_cselect_b32 s12, -2, 4
	s_add_i32 s15, s12, s8
	v_mad_i64_i32 v[82:83], s[12:13], s14, v237, v[172:173]
	s_lshl_b32 s12, s15, 14
	s_add_i32 s15, s4, s12
	s_mov_b32 m0, s15
	s_nop 0
	global_load_lds_dwordx4 v[82:83], off
	v_mad_i64_i32 v[82:83], s[12:13], s14, v237, v[174:175]
	s_add_i32 m0, s15, 0x2000
	s_nop 0
	global_load_lds_dwordx4 v[82:83], off
	s_and_saveexec_b64 s[12:13], s[38:39]
	s_xor_b64 s[26:27], exec, s[12:13]
	s_cbranch_execz .LBB0_438
	s_lshl_b32 s12, s8, 14
	v_or_b32_e32 v70, s12, v183
	ds_read_b128 v[66:69], v70
	ds_read_b128 v[82:85], v70 offset:4096
	v_or_b32_e32 v180, s12, v184
	ds_read_b128 v[176:179], v180
	ds_read_b128 v[188:191], v180 offset:4096
	v_or_b32_e32 v180, s12, v186
	s_waitcnt lgkmcnt(0)
	v_mfma_f32_32x32x16_bf16 v[98:113], v[66:69], v[130:133], 0
	v_mfma_f32_32x32x16_bf16 v[114:129], v[82:85], v[130:133], 0
	v_mfma_f32_32x32x16_bf16 v[82:97], v[82:85], v[146:149], 0
	v_mfma_f32_32x32x16_bf16 v[66:81], v[66:69], v[146:149], 0
	v_mfma_f32_32x32x16_bf16 v[82:97], v[188:191], v[150:153], v[82:97]
	v_mfma_f32_32x32x16_bf16 v[98:113], v[176:179], v[134:137], v[98:113]
	v_mfma_f32_32x32x16_bf16 v[114:129], v[188:191], v[134:137], v[114:129]
	v_mfma_f32_32x32x16_bf16 v[66:81], v[176:179], v[150:153], v[66:81]
	ds_read_b128 v[176:179], v180
	ds_read_b128 v[188:191], v180 offset:4096
	v_or_b32_e32 v180, s12, v187
	s_waitcnt lgkmcnt(0)
	v_mfma_f32_32x32x16_bf16 v[82:97], v[188:191], v[154:157], v[82:97]
	v_mfma_f32_32x32x16_bf16 v[98:113], v[176:179], v[138:141], v[98:113]
	v_mfma_f32_32x32x16_bf16 v[114:129], v[188:191], v[138:141], v[114:129]
	v_mfma_f32_32x32x16_bf16 v[66:81], v[176:179], v[154:157], v[66:81]
	ds_read_b128 v[176:179], v180
	ds_read_b128 v[188:191], v180 offset:4096
	s_waitcnt lgkmcnt(0)
	v_mfma_f32_32x32x16_bf16 v[82:97], v[188:191], v[158:161], v[82:97]
	v_mfma_f32_32x32x16_bf16 v[98:113], v[176:179], v[142:145], v[98:113]
	s_nop 10
	v_exp_f32_e32 v214, v92
	v_or_b32_e32 v92, s12, v185
	v_exp_f32_e32 v196, v86
	v_exp_f32_e32 v202, v88
	v_exp_f32_e32 v208, v90
	v_exp_f32_e32 v220, v94
	v_exp_f32_e32 v242, v96
	v_mfma_f32_32x32x16_bf16 v[114:129], v[188:191], v[142:145], v[114:129]
	v_exp_f32_e32 v181, v99
	v_exp_f32_e32 v189, v100
	v_exp_f32_e32 v193, v101
	v_exp_f32_e32 v195, v102
	v_exp_f32_e32 v199, v103
	v_exp_f32_e32 v201, v104
	v_exp_f32_e32 v205, v105
	v_mfma_f32_32x32x16_bf16 v[66:81], v[176:179], v[158:161], v[66:81]
	v_exp_f32_e32 v177, v98
	s_nop 2
	v_exp_f32_e32 v191, v116
	v_exp_f32_e32 v197, v118
	v_exp_f32_e32 v203, v120
	v_exp_f32_e32 v209, v122
	v_exp_f32_e32 v190, v84
	v_exp_f32_e32 v116, v85
	s_nop 1
	v_exp_f32_e32 v176, v66
	v_exp_f32_e32 v180, v67
	v_exp_f32_e32 v188, v68
	v_exp_f32_e32 v192, v69
	v_exp_f32_e32 v194, v70
	v_exp_f32_e32 v198, v71
	v_exp_f32_e32 v118, v87
	v_exp_f32_e32 v200, v72
	v_exp_f32_e32 v204, v73
	v_exp_f32_e32 v120, v89
	v_exp_f32_e32 v122, v91
	ds_read_b64_tr_b16 v[84:85], v92 offset:8192
	ds_read_b64_tr_b16 v[86:87], v92 offset:8704
	ds_read_b64_tr_b16 v[88:89], v92 offset:12288
	ds_read_b64_tr_b16 v[90:91], v92 offset:12800
	v_exp_f32_e32 v219, v110
	v_exp_f32_e32 v227, v111
	v_exp_f32_e32 v229, v112
	v_exp_f32_e32 v245, v113
	v_cvt_pk_bf16_f32 v110, v177, v181
	v_cvt_pk_bf16_f32 v111, v189, v193
	v_cvt_pk_bf16_f32 v112, v195, v199
	v_cvt_pk_bf16_f32 v113, v201, v205
	v_exp_f32_e32 v218, v78
	v_exp_f32_e32 v226, v79
	v_exp_f32_e32 v228, v80
	v_exp_f32_e32 v244, v81
	v_cvt_pk_bf16_f32 v78, v176, v180
	v_cvt_pk_bf16_f32 v79, v188, v192
	v_cvt_pk_bf16_f32 v80, v194, v198
	v_cvt_pk_bf16_f32 v81, v200, v204
	s_waitcnt lgkmcnt(0)
; #define MFMA32(a, b, c) __builtin_amdgcn_mfma_f32_32x32x16_bf16((a), (b), (c), 0, 0, 0)
; DI unsigned pack2(float lo, float hi) { f32x2_t v = {lo, hi}; return __builtin_bit_cast(unsigned, __builtin_convertvector(v, bf16x2_t)); }
; DI s16x4 vtr(const char* p) { return __builtin_amdgcn_ds_read_tr16_b64_v4i16((lds_s16x4_ptr)p); }
; template <int MODE, int NQ, int TS, bool FAST = false> ...
;     ...
;       float ls = 0.f;
; #pragma unroll
;       for (int r = 0; r < 16; ++r) {
;         float pa, pb;
;         if (MODE == 1) {
;           if (FAST) { pa = __builtin_amdgcn_exp2f(s0[r]); pb = __builtin_amdgcn_exp2f(s1[r]); }
;           else { pa = __builtin_amdgcn_exp2f(s0[r] - mn); pb = __builtin_amdgcn_exp2f(s1[r] - mn); }
;         }
;         else { pa = __builtin_amdgcn_exp2f(s0[r] - mn); pb = __builtin_amdgcn_exp2f(s1[r] - mn); }
;         s0[r] = pa; s1[r] = pb; ls += pa + pb;
;       }
;       l[nq] += ls;
; #pragma unroll
;       for (int ks = 0; ks < 4; ++ks) {
;         uint4 t4;
;         const int rb = 8 * (ks & 1);
;         if (ks < 2) { t4.x = pack2(s0[rb], s0[rb + 1]); t4.y = pack2(s0[rb + 2], s0[rb + 3]); t4.z = pack2(s0[rb + 4], s0[rb + 5]); t4.w = pack2(s0[rb + 6], s0[rb + 7]); }
;         else { t4.x = pack2(s1[rb], s1[rb + 1]); t4.y = pack2(s1[rb + 2], s1[rb + 3]); t4.z = pack2(s1[rb + 4], s1[rb + 5]); t4.w = pack2(s1[rb + 6], s1[rb + 7]); }
;         pf[nq][ks] = __builtin_bit_cast(bf16x8, t4);
;       }
;     }
;   };
;   auto PV = [&](int slot) {
;     const char* vb_ = lds + slot * 16384 + vfo;
; #pragma unroll
;     for (int ks = 0; ks < 4; ++ks) {
;       const s16x4 a0 = vtr(vb_ + ks * 1024), a1 = vtr(vb_ + ks * 1024 + 512);
;       const s16x4 b0 = vtr(vb_ + 4096 + ks * 1024), b1 = vtr(vb_ + 4096 + ks * 1024 + 512);
;       const bf16x8 v0 = __builtin_shufflevector(a0, a1, 0, 1, 2, 3, 4, 5, 6, 7);
;       const bf16x8 v1 = __builtin_shufflevector(b0, b1, 0, 1, 2, 3, 4, 5, 6, 7);
; #pragma unroll
;       for (int nq = 0; nq < NQ; ++nq) { o[nq][0] = MFMA32(v0, pf[nq][ks], o[nq][0]); o[nq][1] = MFMA32(v1, pf[nq][ks], o[nq][1]); }
;     }
	v_mfma_f32_32x32x16_bf16 v[50:65], v[84:87], v[110:113], v[50:65]
	v_exp_f32_e32 v179, v114
	v_exp_f32_e32 v207, v106
	v_exp_f32_e32 v211, v107
	v_exp_f32_e32 v213, v108
	v_exp_f32_e32 v217, v109
	v_exp_f32_e32 v178, v82
	v_exp_f32_e32 v206, v74
	v_mfma_f32_32x32x16_bf16 v[34:49], v[88:91], v[110:113], v[34:49]
	v_exp_f32_e32 v210, v75
	v_exp_f32_e32 v212, v76
	v_exp_f32_e32 v216, v77
	v_exp_f32_e32 v115, v115
	v_exp_f32_e32 v114, v83
	v_exp_f32_e32 v117, v117
	v_cvt_pk_bf16_f32 v106, v207, v211
	v_mfma_f32_32x32x16_bf16 v[18:33], v[84:87], v[78:81], v[18:33]
	v_cvt_pk_bf16_f32 v107, v213, v217
	v_cvt_pk_bf16_f32 v108, v219, v227
	v_cvt_pk_bf16_f32 v109, v229, v245
	v_add_f32_e64 v66, v176, v178
	v_add_f32_e64 v67, v177, v179
	v_cvt_pk_bf16_f32 v74, v206, v210
	v_cvt_pk_bf16_f32 v75, v212, v216
	v_cvt_pk_bf16_f32 v76, v218, v226
	v_mfma_f32_32x32x16_bf16 v[2:17], v[88:91], v[78:81], v[2:17]
	ds_read_b64_tr_b16 v[84:85], v92 offset:9216
	ds_read_b64_tr_b16 v[86:87], v92 offset:9728
	ds_read_b64_tr_b16 v[88:89], v92 offset:13312
	ds_read_b64_tr_b16 v[90:91], v92 offset:13824
	v_cvt_pk_bf16_f32 v77, v228, v244
	v_exp_f32_e32 v119, v119
	v_pk_add_f32 v[66:67], v[66:67], 0 op_sel_hi:[1,0]
	v_pk_add_f32 v[68:69], v[180:181], v[114:115]
	v_exp_f32_e32 v121, v121
	v_pk_add_f32 v[66:67], v[68:69], v[66:67]
	s_waitcnt lgkmcnt(0)
	v_mfma_f32_32x32x16_bf16 v[50:65], v[84:87], v[106:109], v[50:65]
	v_add_f32_e64 v68, v188, v190
	v_add_f32_e64 v69, v189, v191
	v_exp_f32_e32 v123, v123
	v_pk_add_f32 v[66:67], v[68:69], v[66:67]
	v_pk_add_f32 v[68:69], v[192:193], v[116:117]
	v_exp_f32_e32 v215, v124
	v_pk_add_f32 v[66:67], v[68:69], v[66:67]
	v_pk_add_f32 v[68:69], v[194:195], v[196:197]
	v_mfma_f32_32x32x16_bf16 v[34:49], v[88:91], v[106:109], v[34:49]
	v_add_f32_e64 v66, v68, v66
	v_add_f32_e64 v67, v69, v67
	v_add_f32_e64 v68, v198, v118
	v_add_f32_e64 v69, v199, v119
	v_exp_f32_e32 v125, v125
	v_pk_add_f32 v[66:67], v[68:69], v[66:67]
	v_pk_add_f32 v[68:69], v[200:201], v[202:203]
	v_exp_f32_e32 v124, v93
	v_pk_add_f32 v[66:67], v[68:69], v[66:67]
	v_mfma_f32_32x32x16_bf16 v[18:33], v[84:87], v[74:77], v[18:33]
	v_add_f32_e64 v68, v204, v120
	v_add_f32_e64 v69, v205, v121
	v_exp_f32_e32 v221, v126
	v_cvt_pk_bf16_f32 v102, v179, v115
	v_cvt_pk_bf16_f32 v103, v191, v117
	v_cvt_pk_bf16_f32 v104, v197, v119
	v_cvt_pk_bf16_f32 v105, v203, v121
	v_pk_add_f32 v[66:67], v[68:69], v[66:67]
	v_mfma_f32_32x32x16_bf16 v[2:17], v[88:91], v[74:77], v[2:17]
	ds_read_b64_tr_b16 v[84:85], v92 offset:10240
	ds_read_b64_tr_b16 v[86:87], v92 offset:10752
	ds_read_b64_tr_b16 v[88:89], v92 offset:14336
	ds_read_b64_tr_b16 v[90:91], v92 offset:14848
	v_add_f32_e64 v68, v206, v208
	v_add_f32_e64 v69, v207, v209
	v_cvt_pk_bf16_f32 v70, v178, v114
	v_cvt_pk_bf16_f32 v71, v190, v116
	v_cvt_pk_bf16_f32 v72, v196, v118
	v_cvt_pk_bf16_f32 v73, v202, v120
	v_exp_f32_e32 v127, v127
	v_exp_f32_e32 v126, v95
	v_pk_add_f32 v[66:67], v[68:69], v[66:67]
	v_pk_add_f32 v[68:69], v[210:211], v[122:123]
	s_waitcnt lgkmcnt(0)
	v_mfma_f32_32x32x16_bf16 v[50:65], v[84:87], v[102:105], v[50:65]
	v_exp_f32_e32 v243, v128
	v_pk_add_f32 v[66:67], v[68:69], v[66:67]
	v_pk_add_f32 v[68:69], v[212:213], v[214:215]
	v_exp_f32_e32 v129, v129
	v_exp_f32_e32 v128, v97
	v_pk_add_f32 v[66:67], v[68:69], v[66:67]
	v_pk_add_f32 v[68:69], v[216:217], v[124:125]
	v_mfma_f32_32x32x16_bf16 v[34:49], v[88:91], v[102:105], v[34:49]
	v_add_f32_e64 v66, v68, v66
	v_add_f32_e64 v67, v69, v67
	v_add_f32_e64 v68, v218, v220
	v_add_f32_e64 v69, v219, v221
	v_cvt_pk_bf16_f32 v98, v209, v123
	v_pk_add_f32 v[66:67], v[68:69], v[66:67]
	v_pk_add_f32 v[68:69], v[226:227], v[126:127]
	v_cvt_pk_bf16_f32 v99, v215, v125
	v_pk_add_f32 v[66:67], v[68:69], v[66:67]
	v_mfma_f32_32x32x16_bf16 v[18:33], v[84:87], v[70:73], v[18:33]
	v_add_f32_e64 v68, v228, v242
	v_add_f32_e64 v69, v229, v243
	v_cvt_pk_bf16_f32 v100, v221, v127
	v_add_f32_e64 v66, v68, v66
	v_add_f32_e64 v67, v69, v67
	v_pk_add_f32 v[68:69], v[244:245], v[128:129]
	v_cvt_pk_bf16_f32 v101, v243, v129
	v_pk_add_f32 v[82:83], v[68:69], v[66:67]
	v_cvt_pk_bf16_f32 v66, v208, v122
	v_mfma_f32_32x32x16_bf16 v[2:17], v[88:91], v[70:73], v[2:17]
	ds_read_b64_tr_b16 v[84:85], v92 offset:11264
	ds_read_b64_tr_b16 v[86:87], v92 offset:11776
	ds_read_b64_tr_b16 v[88:89], v92 offset:15360
	ds_read_b64_tr_b16 v[90:91], v92 offset:15872
	v_cvt_pk_bf16_f32 v67, v214, v124
	v_cvt_pk_bf16_f32 v68, v220, v126
	v_cvt_pk_bf16_f32 v69, v242, v128
	s_waitcnt lgkmcnt(0)
	v_mfma_f32_32x32x16_bf16 v[50:65], v[84:87], v[98:101], v[50:65]
	v_mfma_f32_32x32x16_bf16 v[34:49], v[88:91], v[98:101], v[34:49]
	v_mfma_f32_32x32x16_bf16 v[18:33], v[84:87], v[66:69], v[18:33]
	v_mfma_f32_32x32x16_bf16 v[2:17], v[88:91], v[66:69], v[2:17]
